# sliding-window loop software-pipelined: QK of block n+1 issued under the softmax of block n
# speedup vs baseline: 1.0027x; 1.0027x over previous
; #define LAS __attribute__((address_space(3)))
; template <int MODE  > ...
;     ...
;     unsigned long long rem = blockmask;
;     if (!rem) return;
;     int j = 63 - __builtin_clzll(rem); rem &= ~(1ull << j);
;     u32x4 kreg, vreg;
;     kreg = *(const u32x4*)(Kg + (size_t)(64 * j + skey) * 128 + schunk * 8);
;     if (NEEDV) vreg = *(const u32x4*)(Vg + (size_t)(64 * j + skey) * 128 + schunk * 8);
;     int cur = 0;
;     {
;         LAS bf16_t* kb = (LAS bf16_t*)(lds + A_KBUF) + cur * 64 * KPITCH;
;         *(LAS u32x4*)(kb + skey * KPITCH + schunk * 8) = kreg;
;         if (NEEDV) { LAS bf16_t* vb = (LAS bf16_t*)(lds + A_VBUF) + cur * 64 * VPITCH;
;             *(LAS u32x4*)(vb + skey * VPITCH + schunk * 8) = vreg; }
;     }
;     __syncthreads();
;     for (;;) {
;         const bool has_next = rem != 0ull; int jn = 0;
;         if (has_next) { jn = 63 - __builtin_clzll(rem); rem &= ~(1ull << jn);
;             kreg = *(const u32x4*)(Kg + (size_t)(64 * jn + skey) * 128 + schunk * 8);
;             if (NEEDV) vreg = *(const u32x4*)(Vg + (size_t)(64 * jn + skey) * 128 + schunk * 8); }
; __device__ __forceinline__ void attn_unit(unsigned char* ws, LAS unsigned char* lds, int b, int g, int c, const int tid) {
;     ...
;       for (int i = 0; i < 16; ++i) { outl[i * 512] += st.o0[i] * sc; outl[(16 + i) * 512] += st.o1[i] * sc; } }
;     st.m = -1e29f; st.l = 0.f; st.o0 = (f32x16){}; st.o1 = (f32x16){};
;     { const int jlo = c >= 8 ? c - 8 : 0; const unsigned long long upto = (c >= 63) ? ~0ull : ((1ull << (c + 1)) - 1ull);
;       const unsigned long long winmask = upto & ~((1ull << jlo) - 1ull);
;       attn_pass<2>(lds, (const bf16_t*)(ws + WS_KW) + boff, (const bf16_t*)(ws + WS_VW) + boff, winmask, qf, st, t, slope2, 0ull, w, lane, tid, c); }
.LBB0_266:
	s_or_b64 exec, exec, s[4:5]
	ds_read2st64_b32 v[2:3], v199 offset1:8
	ds_read2st64_b32 v[4:5], v199 offset0:128 offset1:136
	s_add_i32 s4, s83, 1
	s_lshl_b64 s[4:5], -1, s4
	s_not_b64 s[4:5], s[4:5]
	s_waitcnt lgkmcnt(0)
	v_fma_f32 v2, v18, v1, v2
	v_fma_f32 v4, v34, v1, v4
	v_fmac_f32_e32 v3, v19, v1
	v_fmac_f32_e32 v5, v35, v1
	ds_write2st64_b32 v199, v2, v3 offset1:8
	ds_write2st64_b32 v199, v4, v5 offset0:128 offset1:136
	ds_read2st64_b32 v[2:3], v199 offset0:16 offset1:24
	ds_read2st64_b32 v[4:5], v199 offset0:144 offset1:152
	s_cmp_lt_u32 s83, 63
	s_cselect_b32 s5, s5, -1
	s_cselect_b32 s4, s4, -1
	s_waitcnt lgkmcnt(0)
	v_fma_f32 v2, v20, v1, v2
	v_fma_f32 v4, v36, v1, v4
	v_fmac_f32_e32 v3, v21, v1
	v_fmac_f32_e32 v5, v37, v1
	ds_write2st64_b32 v199, v2, v3 offset0:16 offset1:24
	ds_write2st64_b32 v199, v4, v5 offset0:144 offset1:152
	ds_read2st64_b32 v[2:3], v199 offset0:32 offset1:40
	ds_read2st64_b32 v[4:5], v199 offset0:160 offset1:168
	v_mov_b32_e32 v34, v178
	v_mov_b32_e32 v16, 0
	v_mov_b32_e32 v15, 0
	s_waitcnt lgkmcnt(0)
	v_fma_f32 v2, v22, v1, v2
	v_fma_f32 v4, v38, v1, v4
	v_fmac_f32_e32 v3, v23, v1
	v_fmac_f32_e32 v5, v39, v1
	ds_write2st64_b32 v199, v2, v3 offset0:32 offset1:40
	ds_write2st64_b32 v199, v4, v5 offset0:160 offset1:168
	ds_read2st64_b32 v[2:3], v199 offset0:48 offset1:56
	ds_read2st64_b32 v[4:5], v199 offset0:176 offset1:184
	v_mov_b32_e32 v14, 0
	v_mov_b32_e32 v13, 0
	v_mov_b32_e32 v12, 0
	s_waitcnt lgkmcnt(0)
	v_fma_f32 v2, v24, v1, v2
	v_fma_f32 v4, v40, v1, v4
	v_fmac_f32_e32 v3, v25, v1
	v_fmac_f32_e32 v5, v41, v1
	ds_write2st64_b32 v199, v2, v3 offset0:48 offset1:56
	ds_write2st64_b32 v199, v4, v5 offset0:176 offset1:184
	ds_read2st64_b32 v[2:3], v199 offset0:64 offset1:72
	ds_read2st64_b32 v[4:5], v199 offset0:192 offset1:200
	v_mov_b32_e32 v11, 0
	v_mov_b32_e32 v10, 0
	v_mov_b32_e32 v9, 0
	s_waitcnt lgkmcnt(0)
	v_fma_f32 v2, v26, v1, v2
	v_fma_f32 v4, v42, v1, v4
	v_fmac_f32_e32 v3, v27, v1
	v_fmac_f32_e32 v5, v43, v1
	ds_write2st64_b32 v199, v2, v3 offset0:64 offset1:72
	ds_write2st64_b32 v199, v4, v5 offset0:192 offset1:200
	ds_read2st64_b32 v[2:3], v199 offset0:80 offset1:88
	ds_read2st64_b32 v[4:5], v199 offset0:208 offset1:216
	v_mov_b32_e32 v8, 0
	v_mov_b32_e32 v7, 0
	v_mov_b32_e32 v6, 0
	s_waitcnt lgkmcnt(0)
	v_fma_f32 v2, v28, v1, v2
	v_fma_f32 v4, v44, v1, v4
	v_fmac_f32_e32 v3, v29, v1
	v_fmac_f32_e32 v5, v45, v1
	ds_write2st64_b32 v199, v2, v3 offset0:80 offset1:88
	ds_write2st64_b32 v199, v4, v5 offset0:208 offset1:216
	ds_read2st64_b32 v[2:3], v199 offset0:96 offset1:104
	ds_read2st64_b32 v[4:5], v199 offset0:224 offset1:232
	v_mov_b32_e32 v29, 0
	v_mov_b32_e32 v28, 0
	v_mov_b32_e32 v27, 0
	s_waitcnt lgkmcnt(0)
	v_fma_f32 v2, v30, v1, v2
	v_fma_f32 v4, v46, v1, v4
	v_fmac_f32_e32 v3, v31, v1
	v_fmac_f32_e32 v5, v47, v1
	ds_write2st64_b32 v199, v2, v3 offset0:96 offset1:104
	ds_write2st64_b32 v199, v4, v5 offset0:224 offset1:232
	ds_read2st64_b32 v[2:3], v199 offset0:112 offset1:120
	ds_read2st64_b32 v[4:5], v199 offset0:240 offset1:248
	v_mov_b32_e32 v31, 0
	v_mov_b32_e32 v30, 0
	v_mov_b32_e32 v26, 0
	s_waitcnt lgkmcnt(0)
	v_fma_f32 v2, v32, v1, v2
	v_fma_f32 v4, v48, v1, v4
	v_fmac_f32_e32 v3, v33, v1
	v_fmac_f32_e32 v5, v49, v1
	v_sub_u32_e64 v1, s83, 8 clamp
	ds_write2st64_b32 v199, v2, v3 offset0:112 offset1:120
	v_readfirstlane_b32 s14, v1
	s_lshl_b64 s[14:15], -1, s14
	s_and_b64 s[4:5], s[4:5], s[14:15]
	ds_write2st64_b32 v199, v4, v5 offset0:240 offset1:248
	v_mov_b32_e32 v1, v179
	s_cmp_eq_u64 s[4:5], 0
	v_mov_b32_e32 v5, 0
	v_mov_b32_e32 v4, 0
	v_mov_b32_e32 v3, 0
	v_mov_b32_e32 v2, 0
	v_mov_b32_e32 v33, 0
	v_mov_b32_e32 v32, 0
	v_mov_b32_e32 v25, 0
	v_mov_b32_e32 v24, 0
	v_mov_b32_e32 v23, 0
	v_mov_b32_e32 v22, 0
	v_mov_b32_e32 v21, 0
	v_mov_b32_e32 v20, 0
	v_mov_b32_e32 v19, 0
	v_mov_b32_e32 v18, 0
	v_mov_b32_e32 v35, 0
	s_cbranch_scc1 .LBB0_285
	s_lshl_b32 s16, s22, 1
	s_add_u32 s14, s47, s16
	s_addc_u32 s15, s48, 0
	s_add_u32 s16, s49, s16
	s_flbit_i32_b64 s18, s[4:5]
	v_ashrrev_i32_e32 v161, 3, v34
	s_addc_u32 s17, s82, 0
	s_xor_b32 s20, s18, 63
	v_lshl_add_u32 v2, s20, 6, v161
	v_ashrrev_i32_e32 v3, 31, v2
	v_lshlrev_b64 v[2:3], 8, v[2:3]
	v_lshlrev_b32_e32 v6, 4, v34
	v_lshl_add_u64 v[4:5], s[16:17], 0, v[2:3]
	v_and_b32_e32 v16, 0x70, v6
	v_mov_b32_e32 v17, v0
	v_lshl_add_u64 v[4:5], v[4:5], 0, v[16:17]
	v_lshl_add_u64 v[2:3], s[14:15], 0, v[2:3]
	v_lshl_add_u64 v[2:3], v[2:3], 0, v[16:17]
	s_waitcnt vmcnt(0)
	v_ashrrev_i32_e32 v18, 5, v1
	v_lshrrev_b32_e32 v34, 2, v1
	v_lshlrev_b32_e32 v37, 2, v18
	v_and_b32_e32 v19, 31, v1
	v_lshlrev_b32_e32 v20, 2, v1
	v_and_b32_e32 v21, 16, v1
	v_lshlrev_b32_e32 v22, 3, v1
	v_mov_b32_e32 v14, v0
	v_mov_b32_e32 v15, v0
	s_movk_i32 s18, 0x90
	v_and_or_b32 v34, v34, 3, v37
	v_mov_b32_e32 v1, v0
	v_mov_b32_e32 v2, v0
	v_mov_b32_e32 v3, v0
	v_mov_b32_e32 v4, v0
	v_mov_b32_e32 v5, v0
	v_mov_b32_e32 v6, v0
	v_mov_b32_e32 v7, v0
	v_mov_b32_e32 v8, v0
	v_mov_b32_e32 v9, v0
	v_mov_b32_e32 v10, v0
	v_mov_b32_e32 v11, v0
	v_mov_b32_e32 v12, v0
	v_mov_b32_e32 v13, v0
	v_mul_lo_u32 v35, v161, s18
	v_mul_lo_u32 v36, v161, s70
	v_mul_u32_u24_e32 v38, 0x90, v19
	v_bitop3_b32 v164, v20, s66, v240 bitop3:0x6c
	v_lshlrev_b32_e32 v39, 1, v21
	v_and_b32_e32 v40, 24, v22
	v_lshlrev_b32_e32 v41, 4, v18
	v_mov_b64_e32 v[32:33], v[14:15]
	v_mul_lo_u32 v34, v34, s70
	v_mov_b64_e32 v[30:31], v[12:13]
	v_mov_b64_e32 v[28:29], v[10:11]
	v_mov_b64_e32 v[26:27], v[8:9]
	v_mov_b64_e32 v[24:25], v[6:7]
	v_mov_b64_e32 v[22:23], v[4:5]
	v_mov_b64_e32 v[20:21], v[2:3]
	v_mov_b64_e32 v[18:19], v[0:1]
	v_add3_u32 v165, 0, v35, v16
	v_add3_u32 v166, 0, v36, v16
	v_lshl_add_u64 v[140:141], s[14:15], 0, v[16:17]
	v_add_u32_e32 v34, 0, v34
	s_lshl_b64 s[14:15], 1, s20
	v_lshl_add_u64 v[142:143], s[16:17], 0, v[16:17]
	v_mov_b64_e32 v[16:17], v[14:15]
	v_mul_f32_e32 v162, 0xc3ffc000, v186
	s_mov_b32 s22, 0
	v_mov_b32_e32 v192, 0xefa18f08
	v_mov_b32_e32 v190, 0
	v_sub_u32_e32 v167, v37, v188
	v_add3_u32 v188, 0, v38, v41
	s_add_i32 s23, s83, -8
	v_add3_u32 v191, v34, v39, v40
	s_andn2_b64 s[14:15], s[4:5], s[14:15]
	v_mov_b64_e32 v[14:15], v[12:13]
	v_mov_b64_e32 v[12:13], v[10:11]
	v_mov_b64_e32 v[10:11], v[8:9]
	v_mov_b64_e32 v[8:9], v[6:7]
	v_mov_b64_e32 v[6:7], v[4:5]
	v_mov_b64_e32 v[4:5], v[2:3]
	v_mov_b64_e32 v[2:3], v[0:1]
	s_mov_b64 s[16:17], s[14:15]
	s_mov_b32 s18, 0
	s_cmp_eq_u64 s[16:17], 0
	s_cbranch_scc1 .Lp2_nob1_1
	s_flbit_i32_b64 s62, s[16:17]
	s_xor_b32 s62, s62, 63
	s_lshl_b64 s[4:5], 1, s62
	s_andn2_b64 s[16:17], s[16:17], s[4:5]
	v_lshl_add_u32 v50, s62, 6, v161
	v_ashrrev_i32_e32 v51, 31, v50
	v_lshlrev_b64 v[50:51], 8, v[50:51]
	v_lshl_add_u64 v[52:53], v[142:143], 0, v[50:51]
	v_lshl_add_u64 v[50:51], v[140:141], 0, v[50:51]
	global_load_dwordx4 v[226:229], v[52:53], off
	global_load_dwordx4 v[230:233], v[50:51], off
	s_mov_b32 s18, 1
	s_waitcnt vmcnt(2)
	s_branch .Lp2_prew_2

; #define LAS __attribute__((address_space(3)))
; template <int MODE  > ...
;     ...
;     {
;         LAS bf16_t* kb = (LAS bf16_t*)(lds + A_KBUF) + cur * 64 * KPITCH;
;         *(LAS u32x4*)(kb + skey * KPITCH + schunk * 8) = kreg;
;         if (NEEDV) { LAS bf16_t* vb = (LAS bf16_t*)(lds + A_VBUF) + cur * 64 * VPITCH;
;             *(LAS u32x4*)(vb + skey * VPITCH + schunk * 8) = vreg; }
;     }
;     __syncthreads();
;     ...
;             const LAS bf16_t* kb = (const LAS bf16_t*)(lds + A_KBUF) + cur * 64 * KPITCH;
;             constexpr int STEP = CMPM ? 16 : 1;
;             const int Bint = CMPM ? (1024 * j + 31 - t + 64 * h) : (64 * j - t + 4 * h);
;             const float sl = slope2 * (float)STEP;
;             const float mref = st.m; const bool fresh = !(mref > -1e28f);
;             const float mest = fresh ? 0.f : mref;
;             const float basef = selbit ? (slope2 * (float)Bint - mest) : -1e30f;
;             int ptype;
;             if (MODE == 1) ptype = (j == cblk) ? 1 : 0;
;             else if (MODE == 2) ptype = (j == cblk) ? 1 : ((j == cblk - 8) ? 2 : 0);
;             else ptype = (64 * j + 63 <= 4 * cblk - 2) ? 0 : 1;
;             f32x16 s0, s1;
;             { const float sl2 = sl + sl, sl3 = sl2 + sl;
; #pragma unroll
;               for (int g8 = 0; g8 < 4; ++g8) {
;                   const float b0 = __builtin_fmaf(sl, (float)(8 * g8), basef), b1 = __builtin_fmaf(sl, (float)(8 * g8 + 32), basef);
;                   s0[4 * g8] = b0; s0[4 * g8 + 1] = b0 + sl; s0[4 * g8 + 2] = b0 + sl2; s0[4 * g8 + 3] = b0 + sl3;
;                   s1[4 * g8] = b1; s1[4 * g8 + 1] = b1 + sl; s1[4 * g8 + 2] = b1 + sl2; s1[4 * g8 + 3] = b1 + sl3;
;               } }
;             if (ptype == 1) {
;                 const float thr = 0.5f * slope2 - mest;
; #pragma unroll
;                 for (int i = 0; i < 16; ++i) { s0[i] = (s0[i] < thr) ? s0[i] : -1e30f; s1[i] = (s1[i] < thr) ? s1[i] : -1e30f; }
;             } else if (ptype == 2) {
;                 const float thr = -511.5f * slope2 - mest;
; #pragma unroll
;                 for (int i = 0; i < 16; ++i) { s0[i] = (s0[i] > thr) ? s0[i] : -1e30f; s1[i] = (s1[i] > thr) ? s1[i] : -1e30f; }
;             }
.Lp2_prew_2:
	s_waitcnt lgkmcnt(0)
	ds_write_b128 v165, v[220:223]
	ds_write_b128 v166, v[248:251] offset:18432
	s_waitcnt lgkmcnt(0)
	s_barrier
	s_mul_i32 vcc_lo, s22, 0x2400
	v_add_u32_e32 v254, vcc_lo, v188
	ds_read_b128 v[66:69], v254
	ds_read_b128 v[70:73], v254 offset:4608
	ds_read_b128 v[74:77], v254 offset:32
	ds_read_b128 v[78:81], v254 offset:4640
	ds_read_b128 v[82:85], v254 offset:64
	ds_read_b128 v[86:89], v254 offset:4672
	ds_read_b128 v[90:93], v254 offset:96
	ds_read_b128 v[94:97], v254 offset:4704
	v_lshl_add_u32 v1, s20, 6, v167
	v_cvt_f32_i32_e32 v50, v1
	v_cmp_nlt_f32_e64 s[14:15], s71, v192
	s_cmp_eq_u32 s20, s23
	s_cselect_b32 s21, 2, 0
	s_cmp_lg_u32 s20, s83
	s_cselect_b32 s68, s21, 1
	s_cmp_eq_u32 s68, 0
	v_cndmask_b32_e64 v224, v192, 0, s[14:15]
	v_fma_f32 v62, v186, v50, -v224
	v_fma_f32 v34, 0, v186, v62
	v_fmamk_f32 v38, v186, 0x41000000, v62
	v_fmamk_f32 v42, v186, 0x41800000, v62
	v_fmamk_f32 v46, v186, 0x41c00000, v62
	v_fmamk_f32 v50, v186, 0x42000000, v62
	v_fmamk_f32 v54, v186, 0x42200000, v62
	v_fmamk_f32 v58, v186, 0x42400000, v62
	v_fmac_f32_e32 v62, 0x42600000, v186
	v_add_f32_e32 v35, v186, v34
	v_add_f32_e32 v36, v187, v34
	v_add_f32_e32 v37, v163, v34
	v_add_f32_e32 v39, v186, v38
	v_add_f32_e32 v40, v187, v38
	v_add_f32_e32 v41, v163, v38
	v_add_f32_e32 v43, v186, v42
	v_add_f32_e32 v44, v187, v42
	v_add_f32_e32 v45, v163, v42
	v_add_f32_e32 v47, v186, v46
	v_add_f32_e32 v48, v187, v46
	v_add_f32_e32 v49, v163, v46
	v_add_f32_e32 v51, v186, v50
	v_add_f32_e32 v52, v187, v50
	v_add_f32_e32 v53, v163, v50
	v_add_f32_e32 v55, v186, v54
	v_add_f32_e32 v56, v187, v54
	v_add_f32_e32 v57, v163, v54
	v_add_f32_e32 v59, v186, v58
	v_add_f32_e32 v60, v187, v58
	v_add_f32_e32 v61, v163, v58
	v_add_f32_e32 v63, v186, v62
	v_add_f32_e32 v64, v187, v62
	v_add_f32_e32 v65, v163, v62
	s_cbranch_scc1 .Lp2_initdone_3
	s_cmp_eq_u32 s68, 1
	s_cbranch_scc1 .Lp2_edge1_4
	v_sub_f32_e32 v253, v162, v224
	v_cmp_gt_f32_e32 vcc, v34, v253
	s_nop 1
	v_cndmask_b32_e32 v34, v241, v34, vcc
	v_cmp_gt_f32_e32 vcc, v35, v253
	s_nop 1
	v_cndmask_b32_e32 v35, v241, v35, vcc
	v_cmp_gt_f32_e32 vcc, v36, v253
	s_nop 1
	v_cndmask_b32_e32 v36, v241, v36, vcc
	v_cmp_gt_f32_e32 vcc, v37, v253
	s_nop 1
	v_cndmask_b32_e32 v37, v241, v37, vcc
	v_cmp_gt_f32_e32 vcc, v38, v253
	s_nop 1
	v_cndmask_b32_e32 v38, v241, v38, vcc
	v_cmp_gt_f32_e32 vcc, v39, v253
	s_nop 1
	v_cndmask_b32_e32 v39, v241, v39, vcc
	v_cmp_gt_f32_e32 vcc, v40, v253
	s_nop 1
	v_cndmask_b32_e32 v40, v241, v40, vcc
	v_cmp_gt_f32_e32 vcc, v41, v253
	s_nop 1
	v_cndmask_b32_e32 v41, v241, v41, vcc
	v_cmp_gt_f32_e32 vcc, v42, v253
	s_nop 1
	v_cndmask_b32_e32 v42, v241, v42, vcc
	v_cmp_gt_f32_e32 vcc, v43, v253
	s_nop 1
	v_cndmask_b32_e32 v43, v241, v43, vcc
	v_cmp_gt_f32_e32 vcc, v44, v253
	s_nop 1
	v_cndmask_b32_e32 v44, v241, v44, vcc
	v_cmp_gt_f32_e32 vcc, v45, v253
	s_nop 1
	v_cndmask_b32_e32 v45, v241, v45, vcc
	v_cmp_gt_f32_e32 vcc, v46, v253
	s_nop 1
	v_cndmask_b32_e32 v46, v241, v46, vcc
	v_cmp_gt_f32_e32 vcc, v47, v253
	s_nop 1
	v_cndmask_b32_e32 v47, v241, v47, vcc
	v_cmp_gt_f32_e32 vcc, v48, v253
	s_nop 1
	v_cndmask_b32_e32 v48, v241, v48, vcc
	v_cmp_gt_f32_e32 vcc, v49, v253
	s_nop 1
	v_cndmask_b32_e32 v49, v241, v49, vcc
	v_cmp_gt_f32_e32 vcc, v50, v253
	s_nop 1
	v_cndmask_b32_e32 v50, v241, v50, vcc
	v_cmp_gt_f32_e32 vcc, v51, v253
	s_nop 1
	v_cndmask_b32_e32 v51, v241, v51, vcc
	v_cmp_gt_f32_e32 vcc, v52, v253
	s_nop 1
	v_cndmask_b32_e32 v52, v241, v52, vcc
	v_cmp_gt_f32_e32 vcc, v53, v253
	s_nop 1
	v_cndmask_b32_e32 v53, v241, v53, vcc
	v_cmp_gt_f32_e32 vcc, v54, v253
	s_nop 1
	v_cndmask_b32_e32 v54, v241, v54, vcc
	v_cmp_gt_f32_e32 vcc, v55, v253
	s_nop 1
	v_cndmask_b32_e32 v55, v241, v55, vcc
	v_cmp_gt_f32_e32 vcc, v56, v253
	s_nop 1
	v_cndmask_b32_e32 v56, v241, v56, vcc
	v_cmp_gt_f32_e32 vcc, v57, v253
	s_nop 1
	v_cndmask_b32_e32 v57, v241, v57, vcc
	v_cmp_gt_f32_e32 vcc, v58, v253
	s_nop 1
	v_cndmask_b32_e32 v58, v241, v58, vcc
	v_cmp_gt_f32_e32 vcc, v59, v253
	s_nop 1
	v_cndmask_b32_e32 v59, v241, v59, vcc
	v_cmp_gt_f32_e32 vcc, v60, v253
	s_nop 1
	v_cndmask_b32_e32 v60, v241, v60, vcc
	v_cmp_gt_f32_e32 vcc, v61, v253
	s_nop 1
	v_cndmask_b32_e32 v61, v241, v61, vcc
	v_cmp_gt_f32_e32 vcc, v62, v253
	s_nop 1
	v_cndmask_b32_e32 v62, v241, v62, vcc
	v_cmp_gt_f32_e32 vcc, v63, v253
	s_nop 1
	v_cndmask_b32_e32 v63, v241, v63, vcc
	v_cmp_gt_f32_e32 vcc, v64, v253
	s_nop 1
	v_cndmask_b32_e32 v64, v241, v64, vcc
	v_cmp_gt_f32_e32 vcc, v65, v253
	s_nop 1
	v_cndmask_b32_e32 v65, v241, v65, vcc
	s_branch .Lp2_initdone_3
; #define LAS __attribute__((address_space(3)))
; template <int MODE  > ...
;     ...
;             if (ptype == 1) {
;                 const float thr = 0.5f * slope2 - mest;
; #pragma unroll
;                 for (int i = 0; i < 16; ++i) { s0[i] = (s0[i] < thr) ? s0[i] : -1e30f; s1[i] = (s1[i] < thr) ? s1[i] : -1e30f; }
;             } else if (ptype == 2) {
;                 const float thr = -511.5f * slope2 - mest;
; #pragma unroll
;                 for (int i = 0; i < 16; ++i) { s0[i] = (s0[i] > thr) ? s0[i] : -1e30f; s1[i] = (s1[i] > thr) ? s1[i] : -1e30f; }
;             }
; #pragma unroll
;             for (int kk = 0; kk < 4; ++kk) {
;                 const bf16x8 k0 = *(const LAS bf16x8*)(kb + col * KPITCH + kk * 16 + h * 8);
;                 const bf16x8 k1 = *(const LAS bf16x8*)(kb + (32 + col) * KPITCH + kk * 16 + h * 8);
;                 s0 = __builtin_amdgcn_mfma_f32_32x32x16_bf16(k0, qf[kk], s0, 0, 0, 0);
;                 s1 = __builtin_amdgcn_mfma_f32_32x32x16_bf16(k1, qf[kk], s1, 0, 0, 0);
;             }
;     ...
;         if (has_next) {
;             LAS bf16_t* kb = (LAS bf16_t*)(lds + A_KBUF) + (cur ^ 1) * 64 * KPITCH;
;             *(LAS u32x4*)(kb + skey * KPITCH + schunk * 8) = kreg;
;             if (NEEDV) { LAS bf16_t* vb = (LAS bf16_t*)(lds + A_VBUF) + (cur ^ 1) * 64 * VPITCH;
;                 *(LAS u32x4*)(vb + skey * VPITCH + schunk * 8) = vreg; }
.Lp2_edge1_4:
	v_sub_f32_e32 v253, v189, v224
	v_cmp_lt_f32_e32 vcc, v34, v253
	s_nop 1
	v_cndmask_b32_e32 v34, v241, v34, vcc
	v_cmp_lt_f32_e32 vcc, v35, v253
	s_nop 1
	v_cndmask_b32_e32 v35, v241, v35, vcc
	v_cmp_lt_f32_e32 vcc, v36, v253
	s_nop 1
	v_cndmask_b32_e32 v36, v241, v36, vcc
	v_cmp_lt_f32_e32 vcc, v37, v253
	s_nop 1
	v_cndmask_b32_e32 v37, v241, v37, vcc
	v_cmp_lt_f32_e32 vcc, v38, v253
	s_nop 1
	v_cndmask_b32_e32 v38, v241, v38, vcc
	v_cmp_lt_f32_e32 vcc, v39, v253
	s_nop 1
	v_cndmask_b32_e32 v39, v241, v39, vcc
	v_cmp_lt_f32_e32 vcc, v40, v253
	s_nop 1
	v_cndmask_b32_e32 v40, v241, v40, vcc
	v_cmp_lt_f32_e32 vcc, v41, v253
	s_nop 1
	v_cndmask_b32_e32 v41, v241, v41, vcc
	v_cmp_lt_f32_e32 vcc, v42, v253
	s_nop 1
	v_cndmask_b32_e32 v42, v241, v42, vcc
	v_cmp_lt_f32_e32 vcc, v43, v253
	s_nop 1
	v_cndmask_b32_e32 v43, v241, v43, vcc
	v_cmp_lt_f32_e32 vcc, v44, v253
	s_nop 1
	v_cndmask_b32_e32 v44, v241, v44, vcc
	v_cmp_lt_f32_e32 vcc, v45, v253
	s_nop 1
	v_cndmask_b32_e32 v45, v241, v45, vcc
	v_cmp_lt_f32_e32 vcc, v46, v253
	s_nop 1
	v_cndmask_b32_e32 v46, v241, v46, vcc
	v_cmp_lt_f32_e32 vcc, v47, v253
	s_nop 1
	v_cndmask_b32_e32 v47, v241, v47, vcc
	v_cmp_lt_f32_e32 vcc, v48, v253
	s_nop 1
	v_cndmask_b32_e32 v48, v241, v48, vcc
	v_cmp_lt_f32_e32 vcc, v49, v253
	s_nop 1
	v_cndmask_b32_e32 v49, v241, v49, vcc
	v_cmp_lt_f32_e32 vcc, v50, v253
	s_nop 1
	v_cndmask_b32_e32 v50, v241, v50, vcc
	v_cmp_lt_f32_e32 vcc, v51, v253
	s_nop 1
	v_cndmask_b32_e32 v51, v241, v51, vcc
	v_cmp_lt_f32_e32 vcc, v52, v253
	s_nop 1
	v_cndmask_b32_e32 v52, v241, v52, vcc
	v_cmp_lt_f32_e32 vcc, v53, v253
	s_nop 1
	v_cndmask_b32_e32 v53, v241, v53, vcc
	v_cmp_lt_f32_e32 vcc, v54, v253
	s_nop 1
	v_cndmask_b32_e32 v54, v241, v54, vcc
	v_cmp_lt_f32_e32 vcc, v55, v253
	s_nop 1
	v_cndmask_b32_e32 v55, v241, v55, vcc
	v_cmp_lt_f32_e32 vcc, v56, v253
	s_nop 1
	v_cndmask_b32_e32 v56, v241, v56, vcc
	v_cmp_lt_f32_e32 vcc, v57, v253
	s_nop 1
	v_cndmask_b32_e32 v57, v241, v57, vcc
	v_cmp_lt_f32_e32 vcc, v58, v253
	s_nop 1
	v_cndmask_b32_e32 v58, v241, v58, vcc
	v_cmp_lt_f32_e32 vcc, v59, v253
	s_nop 1
	v_cndmask_b32_e32 v59, v241, v59, vcc
	v_cmp_lt_f32_e32 vcc, v60, v253
	s_nop 1
	v_cndmask_b32_e32 v60, v241, v60, vcc
	v_cmp_lt_f32_e32 vcc, v61, v253
	s_nop 1
	v_cndmask_b32_e32 v61, v241, v61, vcc
	v_cmp_lt_f32_e32 vcc, v62, v253
	s_nop 1
	v_cndmask_b32_e32 v62, v241, v62, vcc
	v_cmp_lt_f32_e32 vcc, v63, v253
	s_nop 1
	v_cndmask_b32_e32 v63, v241, v63, vcc
	v_cmp_lt_f32_e32 vcc, v64, v253
	s_nop 1
	v_cndmask_b32_e32 v64, v241, v64, vcc
	v_cmp_lt_f32_e32 vcc, v65, v253
	s_nop 1
	v_cndmask_b32_e32 v65, v241, v65, vcc
.Lp2_initdone_3:
	s_nop 1
	s_waitcnt lgkmcnt(7)
	v_mfma_f32_32x32x16_bf16 v[34:49], v[66:69], v[144:147], v[34:49]
	s_waitcnt lgkmcnt(6)
	v_mfma_f32_32x32x16_bf16 v[50:65], v[70:73], v[144:147], v[50:65]
	s_waitcnt lgkmcnt(5)
	v_mfma_f32_32x32x16_bf16 v[34:49], v[74:77], v[148:151], v[34:49]
	s_waitcnt lgkmcnt(4)
	v_mfma_f32_32x32x16_bf16 v[50:65], v[78:81], v[148:151], v[50:65]
	s_waitcnt lgkmcnt(3)
	v_mfma_f32_32x32x16_bf16 v[34:49], v[82:85], v[152:155], v[34:49]
	s_waitcnt lgkmcnt(2)
	v_mfma_f32_32x32x16_bf16 v[50:65], v[86:89], v[152:155], v[50:65]
	s_waitcnt lgkmcnt(1)
	v_mfma_f32_32x32x16_bf16 v[34:49], v[90:93], v[156:159], v[34:49]
	s_waitcnt lgkmcnt(0)
	v_mfma_f32_32x32x16_bf16 v[50:65], v[94:97], v[156:159], v[50:65]
	s_cmp_eq_u32 s18, 0
	s_cbranch_scc1 .Lp2_nok1_5
	s_waitcnt vmcnt(1)
	v_add_u32_e32 v234, 0x2400, v165
	ds_write_b128 v234, v[226:229]

; #define LAS __attribute__((address_space(3)))
; template <int MODE  > ...
;     ...
;         const bool has_next = rem != 0ull; int jn = 0;
;         if (has_next) { jn = 63 - __builtin_clzll(rem); rem &= ~(1ull << jn);
;             kreg = *(const u32x4*)(Kg + (size_t)(64 * jn + skey) * 128 + schunk * 8);
;             if (NEEDV) vreg = *(const u32x4*)(Vg + (size_t)(64 * jn + skey) * 128 + schunk * 8); }
;         const bool selbit = (MODE == 1) ? (((selmask >> j) & 1ull) != 0ull) : true;
;         bool active = true;
;         if (MODE == 1) active = __builtin_amdgcn_ballot_w64(selbit) != 0ull;
;         if (active) {
;             const LAS bf16_t* kb = (const LAS bf16_t*)(lds + A_KBUF) + cur * 64 * KPITCH;
;             constexpr int STEP = CMPM ? 16 : 1;
;             const int Bint = CMPM ? (1024 * j + 31 - t + 64 * h) : (64 * j - t + 4 * h);
;             const float sl = slope2 * (float)STEP;
;             const float mref = st.m; const bool fresh = !(mref > -1e28f);
;             const float mest = fresh ? 0.f : mref;
;             const float basef = selbit ? (slope2 * (float)Bint - mest) : -1e30f;
;             int ptype;
;             if (MODE == 1) ptype = (j == cblk) ? 1 : 0;
;             else if (MODE == 2) ptype = (j == cblk) ? 1 : ((j == cblk - 8) ? 2 : 0);
;             else ptype = (64 * j + 63 <= 4 * cblk - 2) ? 0 : 1;
;             f32x16 s0, s1;
;             { const float sl2 = sl + sl, sl3 = sl2 + sl;
; #pragma unroll
;               for (int g8 = 0; g8 < 4; ++g8) {
;                   const float b0 = __builtin_fmaf(sl, (float)(8 * g8), basef), b1 = __builtin_fmaf(sl, (float)(8 * g8 + 32), basef);
;                   s0[4 * g8] = b0; s0[4 * g8 + 1] = b0 + sl; s0[4 * g8 + 2] = b0 + sl2; s0[4 * g8 + 3] = b0 + sl3;
;                   s1[4 * g8] = b1; s1[4 * g8 + 1] = b1 + sl; s1[4 * g8 + 2] = b1 + sl2; s1[4 * g8 + 3] = b1 + sl3;
;               } }
;             if (ptype == 1) {
;                 const float thr = 0.5f * slope2 - mest;
; #pragma unroll
;                 for (int i = 0; i < 16; ++i) { s0[i] = (s0[i] < thr) ? s0[i] : -1e30f; s1[i] = (s1[i] < thr) ? s1[i] : -1e30f; }
;             } else if (ptype == 2) {
;                 const float thr = -511.5f * slope2 - mest;
; #pragma unroll
;                 for (int i = 0; i < 16; ++i) { s0[i] = (s0[i] > thr) ? s0[i] : -1e30f; s1[i] = (s1[i] > thr) ? s1[i] : -1e30f; }
;             }
.Lp2_int0:
	s_mov_b32 s19, 0
	s_cmp_eq_u64 s[16:17], 0
	s_cbranch_scc1 .Lp2_noload_6
	s_flbit_i32_b64 s4, s[16:17]
	s_xor_b32 s4, s4, 63
	s_lshl_b64 vcc, 1, s4
	s_andn2_b64 s[16:17], s[16:17], vcc
	s_mov_b32 s19, 1
	v_lshl_add_u32 v98, s4, 6, v161
	v_ashrrev_i32_e32 v99, 31, v98
	v_lshlrev_b64 v[98:99], 8, v[98:99]
	v_lshl_add_u64 v[100:101], v[142:143], 0, v[98:99]
	v_lshl_add_u64 v[98:99], v[140:141], 0, v[98:99]
	global_load_dwordx4 v[130:133], v[100:101], off
	global_load_dwordx4 v[134:137], v[98:99], off
.Lp2_noload_6:
	s_xor_b32 vcc_lo, s22, 1
	s_mul_i32 vcc_lo, vcc_lo, 0x2400
	v_add_u32_e32 v254, vcc_lo, v188
	ds_read_b128 v[66:69], v254
	ds_read_b128 v[70:73], v254 offset:4608
	ds_read_b128 v[74:77], v254 offset:32
	ds_read_b128 v[78:81], v254 offset:4640
	ds_read_b128 v[82:85], v254 offset:64
	ds_read_b128 v[86:89], v254 offset:4672
	ds_read_b128 v[90:93], v254 offset:96
	ds_read_b128 v[94:97], v254 offset:4704
	v_lshl_add_u32 v1, s62, 6, v167
	v_cvt_f32_i32_e32 v98, v1
	v_cmp_nlt_f32_e64 s[14:15], s71, v192
	s_cmp_eq_u32 s62, s23
	s_cselect_b32 s21, 2, 0
	s_cmp_lg_u32 s62, s83
	s_cselect_b32 s68, s21, 1
	s_cmp_eq_u32 s68, 0
	v_cndmask_b32_e64 v252, v192, 0, s[14:15]
	v_fma_f32 v110, v186, v98, -v252
	v_fma_f32 v114, 0, v186, v110
	v_fmamk_f32 v118, v186, 0x41000000, v110
	v_fmamk_f32 v122, v186, 0x41800000, v110
	v_fmamk_f32 v126, v186, 0x41c00000, v110
	v_fmamk_f32 v98, v186, 0x42000000, v110
	v_fmamk_f32 v102, v186, 0x42200000, v110
	v_fmamk_f32 v106, v186, 0x42400000, v110
	v_fmac_f32_e32 v110, 0x42600000, v186
	v_add_f32_e32 v115, v186, v114
	v_add_f32_e32 v116, v187, v114
	v_add_f32_e32 v117, v163, v114
	v_add_f32_e32 v119, v186, v118
	v_add_f32_e32 v120, v187, v118
	v_add_f32_e32 v121, v163, v118
	v_add_f32_e32 v123, v186, v122
	v_add_f32_e32 v124, v187, v122
	v_add_f32_e32 v125, v163, v122
	v_add_f32_e32 v127, v186, v126
	v_add_f32_e32 v128, v187, v126
	v_add_f32_e32 v129, v163, v126
	v_add_f32_e32 v99, v186, v98
	v_add_f32_e32 v100, v187, v98
	v_add_f32_e32 v101, v163, v98
	v_add_f32_e32 v103, v186, v102
	v_add_f32_e32 v104, v187, v102
	v_add_f32_e32 v105, v163, v102
	v_add_f32_e32 v107, v186, v106
	v_add_f32_e32 v108, v187, v106
	v_add_f32_e32 v109, v163, v106
	v_add_f32_e32 v111, v186, v110
	v_add_f32_e32 v112, v187, v110
	v_add_f32_e32 v113, v163, v110
	s_cbranch_scc1 .Lp2_initdone_7
	s_cmp_eq_u32 s68, 1
	s_cbranch_scc1 .Lp2_edge1_8
	v_sub_f32_e32 v253, v162, v252
	v_cmp_gt_f32_e32 vcc, v114, v253
	s_nop 1
	v_cndmask_b32_e32 v114, v241, v114, vcc
	v_cmp_gt_f32_e32 vcc, v115, v253
	s_nop 1
	v_cndmask_b32_e32 v115, v241, v115, vcc
	v_cmp_gt_f32_e32 vcc, v116, v253
	s_nop 1
	v_cndmask_b32_e32 v116, v241, v116, vcc
	v_cmp_gt_f32_e32 vcc, v117, v253
	s_nop 1
	v_cndmask_b32_e32 v117, v241, v117, vcc
	v_cmp_gt_f32_e32 vcc, v118, v253
	s_nop 1
	v_cndmask_b32_e32 v118, v241, v118, vcc
	v_cmp_gt_f32_e32 vcc, v119, v253
	s_nop 1
	v_cndmask_b32_e32 v119, v241, v119, vcc
	v_cmp_gt_f32_e32 vcc, v120, v253
	s_nop 1
	v_cndmask_b32_e32 v120, v241, v120, vcc
	v_cmp_gt_f32_e32 vcc, v121, v253
	s_nop 1
	v_cndmask_b32_e32 v121, v241, v121, vcc
	v_cmp_gt_f32_e32 vcc, v122, v253
	s_nop 1
	v_cndmask_b32_e32 v122, v241, v122, vcc
	v_cmp_gt_f32_e32 vcc, v123, v253
	s_nop 1
	v_cndmask_b32_e32 v123, v241, v123, vcc
	v_cmp_gt_f32_e32 vcc, v124, v253
	s_nop 1
	v_cndmask_b32_e32 v124, v241, v124, vcc
	v_cmp_gt_f32_e32 vcc, v125, v253
	s_nop 1
	v_cndmask_b32_e32 v125, v241, v125, vcc
	v_cmp_gt_f32_e32 vcc, v126, v253
	s_nop 1
	v_cndmask_b32_e32 v126, v241, v126, vcc
	v_cmp_gt_f32_e32 vcc, v127, v253
	s_nop 1
	v_cndmask_b32_e32 v127, v241, v127, vcc
	v_cmp_gt_f32_e32 vcc, v128, v253
	s_nop 1
	v_cndmask_b32_e32 v128, v241, v128, vcc
	v_cmp_gt_f32_e32 vcc, v129, v253
	s_nop 1
	v_cndmask_b32_e32 v129, v241, v129, vcc
	v_cmp_gt_f32_e32 vcc, v98, v253
	s_nop 1
	v_cndmask_b32_e32 v98, v241, v98, vcc
	v_cmp_gt_f32_e32 vcc, v99, v253
	s_nop 1
	v_cndmask_b32_e32 v99, v241, v99, vcc
	v_cmp_gt_f32_e32 vcc, v100, v253
	s_nop 1
	v_cndmask_b32_e32 v100, v241, v100, vcc
	v_cmp_gt_f32_e32 vcc, v101, v253
	s_nop 1
	v_cndmask_b32_e32 v101, v241, v101, vcc
	v_cmp_gt_f32_e32 vcc, v102, v253
	s_nop 1
	v_cndmask_b32_e32 v102, v241, v102, vcc
	v_cmp_gt_f32_e32 vcc, v103, v253
	s_nop 1
	v_cndmask_b32_e32 v103, v241, v103, vcc
	v_cmp_gt_f32_e32 vcc, v104, v253
	s_nop 1
	v_cndmask_b32_e32 v104, v241, v104, vcc
	v_cmp_gt_f32_e32 vcc, v105, v253
	s_nop 1
	v_cndmask_b32_e32 v105, v241, v105, vcc
	v_cmp_gt_f32_e32 vcc, v106, v253
	s_nop 1
	v_cndmask_b32_e32 v106, v241, v106, vcc
	v_cmp_gt_f32_e32 vcc, v107, v253
	s_nop 1
	v_cndmask_b32_e32 v107, v241, v107, vcc
	v_cmp_gt_f32_e32 vcc, v108, v253
	s_nop 1
	v_cndmask_b32_e32 v108, v241, v108, vcc
	v_cmp_gt_f32_e32 vcc, v109, v253
	s_nop 1
	v_cndmask_b32_e32 v109, v241, v109, vcc
	v_cmp_gt_f32_e32 vcc, v110, v253
	s_nop 1
	v_cndmask_b32_e32 v110, v241, v110, vcc
	v_cmp_gt_f32_e32 vcc, v111, v253
	s_nop 1
	v_cndmask_b32_e32 v111, v241, v111, vcc
	v_cmp_gt_f32_e32 vcc, v112, v253
	s_nop 1
	v_cndmask_b32_e32 v112, v241, v112, vcc
	v_cmp_gt_f32_e32 vcc, v113, v253
	s_nop 1
	v_cndmask_b32_e32 v113, v241, v113, vcc
	s_branch .Lp2_initdone_7
; #define LAS __attribute__((address_space(3)))
; __device__ __forceinline__ float shflx(float v, int mask, int lane) { return __builtin_bit_cast(float, __builtin_amdgcn_ds_bpermute(((lane ^ mask) & 63) << 2, __builtin_bit_cast(int, v))); }
; template <int MODE  > ...
;     ...
;             if (ptype == 1) {
;                 const float thr = 0.5f * slope2 - mest;
; #pragma unroll
;                 for (int i = 0; i < 16; ++i) { s0[i] = (s0[i] < thr) ? s0[i] : -1e30f; s1[i] = (s1[i] < thr) ? s1[i] : -1e30f; }
;             } else if (ptype == 2) {
;                 const float thr = -511.5f * slope2 - mest;
; #pragma unroll
;                 for (int i = 0; i < 16; ++i) { s0[i] = (s0[i] > thr) ? s0[i] : -1e30f; s1[i] = (s1[i] > thr) ? s1[i] : -1e30f; }
;             }
; #pragma unroll
;             for (int kk = 0; kk < 4; ++kk) {
;                 const bf16x8 k0 = *(const LAS bf16x8*)(kb + col * KPITCH + kk * 16 + h * 8);
;                 const bf16x8 k1 = *(const LAS bf16x8*)(kb + (32 + col) * KPITCH + kk * 16 + h * 8);
;                 s0 = __builtin_amdgcn_mfma_f32_32x32x16_bf16(k0, qf[kk], s0, 0, 0, 0);
;                 s1 = __builtin_amdgcn_mfma_f32_32x32x16_bf16(k1, qf[kk], s1, 0, 0, 0);
;             }
;             if (MODE != 3) {
;                 float mx = fmaxf(s0[0], s1[0]);
; #pragma unroll
;                 for (int i = 1; i < 16; ++i) mx = fmaxf(mx, fmaxf(s0[i], s1[i]));
;                 mx = fmaxf(mx, shflx(mx, 32, lane));
;                 float alpha = 1.f;
;                 if (__builtin_amdgcn_ballot_w64(fresh || mx > 0.f) != 0ull) {
;                     const float moldr = fresh ? -1e29f : 0.f, mnewr = fmaxf(moldr, mx);
;                     alpha = __builtin_amdgcn_exp2f(moldr - mnewr);
;                     st.m = mest + mnewr;
; #pragma unroll
;                     for (int i = 0; i < 16; ++i) { s0[i] = __builtin_amdgcn_exp2f(s0[i] - mnewr); s1[i] = __builtin_amdgcn_exp2f(s1[i] - mnewr); }
;                     st.o0 *= alpha; st.o1 *= alpha;
;                 } else {
; #pragma unroll
;                     for (int i = 0; i < 16; ++i) { s0[i] = __builtin_amdgcn_exp2f(s0[i]); s1[i] = __builtin_amdgcn_exp2f(s1[i]); }
;                 }
.Lp2_edge1_8:
	v_sub_f32_e32 v253, v189, v252
	v_cmp_lt_f32_e32 vcc, v114, v253
	s_nop 1
	v_cndmask_b32_e32 v114, v241, v114, vcc
	v_cmp_lt_f32_e32 vcc, v115, v253
	s_nop 1
	v_cndmask_b32_e32 v115, v241, v115, vcc
	v_cmp_lt_f32_e32 vcc, v116, v253
	s_nop 1
	v_cndmask_b32_e32 v116, v241, v116, vcc
	v_cmp_lt_f32_e32 vcc, v117, v253
	s_nop 1
	v_cndmask_b32_e32 v117, v241, v117, vcc
	v_cmp_lt_f32_e32 vcc, v118, v253
	s_nop 1
	v_cndmask_b32_e32 v118, v241, v118, vcc
	v_cmp_lt_f32_e32 vcc, v119, v253
	s_nop 1
	v_cndmask_b32_e32 v119, v241, v119, vcc
	v_cmp_lt_f32_e32 vcc, v120, v253
	s_nop 1
	v_cndmask_b32_e32 v120, v241, v120, vcc
	v_cmp_lt_f32_e32 vcc, v121, v253
	s_nop 1
	v_cndmask_b32_e32 v121, v241, v121, vcc
	v_cmp_lt_f32_e32 vcc, v122, v253
	s_nop 1
	v_cndmask_b32_e32 v122, v241, v122, vcc
	v_cmp_lt_f32_e32 vcc, v123, v253
	s_nop 1
	v_cndmask_b32_e32 v123, v241, v123, vcc
	v_cmp_lt_f32_e32 vcc, v124, v253
	s_nop 1
	v_cndmask_b32_e32 v124, v241, v124, vcc
	v_cmp_lt_f32_e32 vcc, v125, v253
	s_nop 1
	v_cndmask_b32_e32 v125, v241, v125, vcc
	v_cmp_lt_f32_e32 vcc, v126, v253
	s_nop 1
	v_cndmask_b32_e32 v126, v241, v126, vcc
	v_cmp_lt_f32_e32 vcc, v127, v253
	s_nop 1
	v_cndmask_b32_e32 v127, v241, v127, vcc
	v_cmp_lt_f32_e32 vcc, v128, v253
	s_nop 1
	v_cndmask_b32_e32 v128, v241, v128, vcc
	v_cmp_lt_f32_e32 vcc, v129, v253
	s_nop 1
	v_cndmask_b32_e32 v129, v241, v129, vcc
	v_cmp_lt_f32_e32 vcc, v98, v253
	s_nop 1
	v_cndmask_b32_e32 v98, v241, v98, vcc
	v_cmp_lt_f32_e32 vcc, v99, v253
	s_nop 1
	v_cndmask_b32_e32 v99, v241, v99, vcc
	v_cmp_lt_f32_e32 vcc, v100, v253
	s_nop 1
	v_cndmask_b32_e32 v100, v241, v100, vcc
	v_cmp_lt_f32_e32 vcc, v101, v253
	s_nop 1
	v_cndmask_b32_e32 v101, v241, v101, vcc
	v_cmp_lt_f32_e32 vcc, v102, v253
	s_nop 1
	v_cndmask_b32_e32 v102, v241, v102, vcc
	v_cmp_lt_f32_e32 vcc, v103, v253
	s_nop 1
	v_cndmask_b32_e32 v103, v241, v103, vcc
	v_cmp_lt_f32_e32 vcc, v104, v253
	s_nop 1
	v_cndmask_b32_e32 v104, v241, v104, vcc
	v_cmp_lt_f32_e32 vcc, v105, v253
	s_nop 1
	v_cndmask_b32_e32 v105, v241, v105, vcc
	v_cmp_lt_f32_e32 vcc, v106, v253
	s_nop 1
	v_cndmask_b32_e32 v106, v241, v106, vcc
	v_cmp_lt_f32_e32 vcc, v107, v253
	s_nop 1
	v_cndmask_b32_e32 v107, v241, v107, vcc
	v_cmp_lt_f32_e32 vcc, v108, v253
	s_nop 1
	v_cndmask_b32_e32 v108, v241, v108, vcc
	v_cmp_lt_f32_e32 vcc, v109, v253
	s_nop 1
	v_cndmask_b32_e32 v109, v241, v109, vcc
	v_cmp_lt_f32_e32 vcc, v110, v253
	s_nop 1
	v_cndmask_b32_e32 v110, v241, v110, vcc
	v_cmp_lt_f32_e32 vcc, v111, v253
	s_nop 1
	v_cndmask_b32_e32 v111, v241, v111, vcc
	v_cmp_lt_f32_e32 vcc, v112, v253
	s_nop 1
	v_cndmask_b32_e32 v112, v241, v112, vcc
	v_cmp_lt_f32_e32 vcc, v113, v253
	s_nop 1
	v_cndmask_b32_e32 v113, v241, v113, vcc
.Lp2_initdone_7:
	v_max3_f32 v234, v34, v35, v36
	v_max3_f32 v234, v234, v37, v38
	v_max3_f32 v234, v234, v39, v40
	v_max3_f32 v234, v234, v41, v42
	v_max3_f32 v234, v234, v43, v44
	v_max3_f32 v234, v234, v45, v46
	v_max3_f32 v234, v234, v47, v48
	v_max3_f32 v235, v50, v51, v52
	v_max3_f32 v235, v235, v53, v54
	v_max3_f32 v235, v235, v55, v56
	v_max3_f32 v235, v235, v57, v58
	v_max3_f32 v235, v235, v59, v60
	v_max3_f32 v235, v235, v61, v62
	v_max3_f32 v235, v235, v63, v64
	v_max3_f32 v234, v234, v49, v65
	v_max_f32_e32 v234, v234, v235
	v_mov_b32_e32 v235, v234
	v_sub_f32_e32 v253, v192, v224
	s_nop 0
	v_permlane32_swap_b32_e32 v235, v234
	v_max_f32_e32 v234, v234, v235
	v_cmp_lt_f32_e32 vcc, 0, v234
	v_cmp_lg_f32_e64 s[14:15], 0, v253
	s_nop 1
	s_or_b64 vcc, s[14:15], vcc
	s_cbranch_vccz .Lp2_fast_9
	v_max_f32_e32 v234, v253, v234
	v_sub_f32_e32 v235, v253, v234
	v_exp_f32_e32 v160, v235
	v_add_f32_e32 v192, v224, v234
	s_waitcnt lgkmcnt(7)
	v_mfma_f32_32x32x16_bf16 v[114:129], v[66:69], v[144:147], v[114:129]
	v_sub_f32_e32 v34, v34, v234
	v_exp_f32_e32 v34, v34
	v_sub_f32_e32 v35, v35, v234
	v_exp_f32_e32 v35, v35
	v_sub_f32_e32 v36, v36, v234
	v_exp_f32_e32 v36, v36
	v_sub_f32_e32 v37, v37, v234
	v_exp_f32_e32 v37, v37
	s_waitcnt lgkmcnt(6)
	v_mfma_f32_32x32x16_bf16 v[98:113], v[70:73], v[144:147], v[98:113]
	v_sub_f32_e32 v38, v38, v234
	v_exp_f32_e32 v38, v38
	v_sub_f32_e32 v39, v39, v234
	v_exp_f32_e32 v39, v39
	v_sub_f32_e32 v40, v40, v234
	v_exp_f32_e32 v40, v40
	v_sub_f32_e32 v41, v41, v234
	v_exp_f32_e32 v41, v41
	s_waitcnt lgkmcnt(5)
	v_mfma_f32_32x32x16_bf16 v[114:129], v[74:77], v[148:151], v[114:129]
	v_sub_f32_e32 v42, v42, v234
	v_exp_f32_e32 v42, v42
	v_sub_f32_e32 v43, v43, v234
	v_exp_f32_e32 v43, v43
	v_sub_f32_e32 v44, v44, v234
	v_exp_f32_e32 v44, v44
	v_sub_f32_e32 v45, v45, v234
	v_exp_f32_e32 v45, v45
	s_waitcnt lgkmcnt(4)
	v_mfma_f32_32x32x16_bf16 v[98:113], v[78:81], v[148:151], v[98:113]
	v_sub_f32_e32 v46, v46, v234
	v_exp_f32_e32 v46, v46
	v_sub_f32_e32 v47, v47, v234
	v_exp_f32_e32 v47, v47
	v_sub_f32_e32 v48, v48, v234
	v_exp_f32_e32 v48, v48
	v_sub_f32_e32 v49, v49, v234
	v_exp_f32_e32 v49, v49
	s_waitcnt lgkmcnt(3)
	v_mfma_f32_32x32x16_bf16 v[114:129], v[82:85], v[152:155], v[114:129]
	v_sub_f32_e32 v50, v50, v234
	v_exp_f32_e32 v50, v50
	v_sub_f32_e32 v51, v51, v234
	v_exp_f32_e32 v51, v51
	v_sub_f32_e32 v52, v52, v234
	v_exp_f32_e32 v52, v52
	v_sub_f32_e32 v53, v53, v234
	v_exp_f32_e32 v53, v53
	s_waitcnt lgkmcnt(2)
	v_mfma_f32_32x32x16_bf16 v[98:113], v[86:89], v[152:155], v[98:113]
	v_sub_f32_e32 v54, v54, v234
	v_exp_f32_e32 v54, v54
	v_sub_f32_e32 v55, v55, v234
	v_exp_f32_e32 v55, v55
	v_sub_f32_e32 v56, v56, v234
	v_exp_f32_e32 v56, v56
	v_sub_f32_e32 v57, v57, v234
	v_exp_f32_e32 v57, v57
	s_waitcnt lgkmcnt(1)
; #define LAS __attribute__((address_space(3)))
; template <int MODE  > ...
;     ...
;                 if (__builtin_amdgcn_ballot_w64(fresh || mx > 0.f) != 0ull) {
;                     const float moldr = fresh ? -1e29f : 0.f, mnewr = fmaxf(moldr, mx);
;                     alpha = __builtin_amdgcn_exp2f(moldr - mnewr);
;                     st.m = mest + mnewr;
; #pragma unroll
;                     for (int i = 0; i < 16; ++i) { s0[i] = __builtin_amdgcn_exp2f(s0[i] - mnewr); s1[i] = __builtin_amdgcn_exp2f(s1[i] - mnewr); }
;                     st.o0 *= alpha; st.o1 *= alpha;
;                 } else {
; #pragma unroll
;                     for (int i = 0; i < 16; ++i) { s0[i] = __builtin_amdgcn_exp2f(s0[i]); s1[i] = __builtin_amdgcn_exp2f(s1[i]); }
;                 }
;                 { typedef float f32x8 __attribute__((ext_vector_type(8)));
;                   const f32x16 t16 = s0 + s1;
;                   const f32x8 t8 = __builtin_shufflevector(t16, t16, 0, 1, 2, 3, 4, 5, 6, 7) + __builtin_shufflevector(t16, t16, 8, 9, 10, 11, 12, 13, 14, 15);
;                   const f32x4 t4 = __builtin_shufflevector(t8, t8, 0, 1, 2, 3) + __builtin_shufflevector(t8, t8, 4, 5, 6, 7);
;                   float ps = (t4[0] + t4[1]) + (t4[2] + t4[3]);
;                   ps += shflx(ps, 32, lane);
;                   st.l = st.l * alpha + ps; }
;                 bf16x8 pf[4];
; #pragma unroll
;                 for (int kk = 0; kk < 4; ++kk) {
;                     u32x4 pw;
;                     if (kk < 2) { pw.x = pk2(s0[8 * kk], s0[8 * kk + 1]); pw.y = pk2(s0[8 * kk + 2], s0[8 * kk + 3]); pw.z = pk2(s0[8 * kk + 4], s0[8 * kk + 5]); pw.w = pk2(s0[8 * kk + 6], s0[8 * kk + 7]); }
;                     else { const int k2 = kk - 2; pw.x = pk2(s1[8 * k2], s1[8 * k2 + 1]); pw.y = pk2(s1[8 * k2 + 2], s1[8 * k2 + 3]); pw.z = pk2(s1[8 * k2 + 4], s1[8 * k2 + 5]); pw.w = pk2(s1[8 * k2 + 6], s1[8 * k2 + 7]); }
;                     pf[kk] = __builtin_bit_cast(bf16x8, pw);
;                 }
;                 const LAS bf16_t* vb = (const LAS bf16_t*)(lds + A_VBUF) + cur * 64 * VPITCH + (4 * h + ((lane & 15) >> 2)) * VPITCH + ((lane >> 4) & 1) * 16 + 4 * (lane & 3);
; #pragma unroll
;                 for (int kk = 0; kk < 4; ++kk) {
;                     typedef short v4i16_t __attribute__((ext_vector_type(4)));
	v_mfma_f32_32x32x16_bf16 v[114:129], v[90:93], v[156:159], v[114:129]
	v_sub_f32_e32 v58, v58, v234
	v_exp_f32_e32 v58, v58
	v_sub_f32_e32 v59, v59, v234
	v_exp_f32_e32 v59, v59
	v_sub_f32_e32 v60, v60, v234
	v_exp_f32_e32 v60, v60
	v_sub_f32_e32 v61, v61, v234
	v_exp_f32_e32 v61, v61
	s_waitcnt lgkmcnt(0)
	v_mfma_f32_32x32x16_bf16 v[98:113], v[94:97], v[156:159], v[98:113]
	v_sub_f32_e32 v62, v62, v234
	v_exp_f32_e32 v62, v62
	v_sub_f32_e32 v63, v63, v234
	v_exp_f32_e32 v63, v63
	v_sub_f32_e32 v64, v64, v234
	v_exp_f32_e32 v64, v64
	v_sub_f32_e32 v65, v65, v234
	v_exp_f32_e32 v65, v65
	v_pk_mul_f32 v[18:19], v[18:19], v[160:161] op_sel_hi:[1,0]
	v_pk_mul_f32 v[20:21], v[20:21], v[160:161] op_sel_hi:[1,0]
	v_pk_mul_f32 v[22:23], v[22:23], v[160:161] op_sel_hi:[1,0]
	v_pk_mul_f32 v[24:25], v[24:25], v[160:161] op_sel_hi:[1,0]
	v_pk_mul_f32 v[26:27], v[26:27], v[160:161] op_sel_hi:[1,0]
	v_pk_mul_f32 v[28:29], v[28:29], v[160:161] op_sel_hi:[1,0]
	v_pk_mul_f32 v[30:31], v[30:31], v[160:161] op_sel_hi:[1,0]
	v_pk_mul_f32 v[32:33], v[32:33], v[160:161] op_sel_hi:[1,0]
	v_pk_mul_f32 v[2:3], v[2:3], v[160:161] op_sel_hi:[1,0]
	v_pk_mul_f32 v[4:5], v[4:5], v[160:161] op_sel_hi:[1,0]
	v_pk_mul_f32 v[6:7], v[6:7], v[160:161] op_sel_hi:[1,0]
	v_pk_mul_f32 v[8:9], v[8:9], v[160:161] op_sel_hi:[1,0]
	v_pk_mul_f32 v[10:11], v[10:11], v[160:161] op_sel_hi:[1,0]
	v_pk_mul_f32 v[12:13], v[12:13], v[160:161] op_sel_hi:[1,0]
	v_pk_mul_f32 v[14:15], v[14:15], v[160:161] op_sel_hi:[1,0]
	v_pk_mul_f32 v[16:17], v[16:17], v[160:161] op_sel_hi:[1,0]
	s_branch .Lp2_pv_10
.Lp2_fast_9:
	s_waitcnt lgkmcnt(7)
	v_mfma_f32_32x32x16_bf16 v[114:129], v[66:69], v[144:147], v[114:129]
	v_exp_f32_e32 v34, v34
	v_exp_f32_e32 v35, v35
	v_exp_f32_e32 v36, v36
	v_exp_f32_e32 v37, v37
	s_waitcnt lgkmcnt(6)
	v_mfma_f32_32x32x16_bf16 v[98:113], v[70:73], v[144:147], v[98:113]
	v_exp_f32_e32 v38, v38
	v_exp_f32_e32 v39, v39
	v_exp_f32_e32 v40, v40
	v_exp_f32_e32 v41, v41
	s_waitcnt lgkmcnt(5)
	v_mfma_f32_32x32x16_bf16 v[114:129], v[74:77], v[148:151], v[114:129]
	v_exp_f32_e32 v42, v42
	v_exp_f32_e32 v43, v43
	v_exp_f32_e32 v44, v44
	v_exp_f32_e32 v45, v45
	s_waitcnt lgkmcnt(4)
	v_mfma_f32_32x32x16_bf16 v[98:113], v[78:81], v[148:151], v[98:113]
	v_exp_f32_e32 v46, v46
	v_exp_f32_e32 v47, v47
	v_exp_f32_e32 v48, v48
	v_exp_f32_e32 v49, v49
	s_waitcnt lgkmcnt(3)
	v_mfma_f32_32x32x16_bf16 v[114:129], v[82:85], v[152:155], v[114:129]
	v_exp_f32_e32 v50, v50
	v_exp_f32_e32 v51, v51
	v_exp_f32_e32 v52, v52
	v_exp_f32_e32 v53, v53
	s_waitcnt lgkmcnt(2)
	v_mfma_f32_32x32x16_bf16 v[98:113], v[86:89], v[152:155], v[98:113]
	v_exp_f32_e32 v54, v54
	v_exp_f32_e32 v55, v55
	v_exp_f32_e32 v56, v56
	v_exp_f32_e32 v57, v57
	s_waitcnt lgkmcnt(1)
	v_mfma_f32_32x32x16_bf16 v[114:129], v[90:93], v[156:159], v[114:129]
	v_exp_f32_e32 v58, v58
	v_exp_f32_e32 v59, v59
	v_exp_f32_e32 v60, v60
	v_exp_f32_e32 v61, v61
	s_waitcnt lgkmcnt(0)
	v_mfma_f32_32x32x16_bf16 v[98:113], v[94:97], v[156:159], v[98:113]
	v_exp_f32_e32 v62, v62
	v_exp_f32_e32 v63, v63
	v_exp_f32_e32 v64, v64
	v_exp_f32_e32 v65, v65
	v_mov_b32_e32 v160, 1.0
.Lp2_pv_10:
	s_mul_i32 vcc_hi, s22, 0x3000
	v_add_u32_e32 v225, vcc_hi, v191
	ds_read_b64_tr_b16 v[66:67], v225 offset:18432
	ds_read_b64_tr_b16 v[68:69], v225 offset:19968
	ds_read_b64_tr_b16 v[70:71], v225 offset:18496
	ds_read_b64_tr_b16 v[72:73], v225 offset:20032
	ds_read_b64_tr_b16 v[74:75], v225 offset:21504
	ds_read_b64_tr_b16 v[76:77], v225 offset:23040
	ds_read_b64_tr_b16 v[78:79], v225 offset:21568
	ds_read_b64_tr_b16 v[80:81], v225 offset:23104
	v_pk_add_f32 v[96:97], v[50:51], v[34:35]
	v_pk_add_f32 v[94:95], v[54:55], v[38:39]
	v_pk_add_f32 v[82:83], v[58:59], v[42:43]
	v_pk_add_f32 v[92:93], v[62:63], v[46:47]
	v_pk_add_f32 v[90:91], v[56:57], v[40:41]
	v_pk_add_f32 v[88:89], v[64:65], v[48:49]
	v_pk_add_f32 v[84:85], v[60:61], v[44:45]
	v_pk_add_f32 v[86:87], v[52:53], v[36:37]
	v_pk_add_f32 v[92:93], v[94:95], v[92:93]
	v_pk_add_f32 v[82:83], v[96:97], v[82:83]
	v_pk_add_f32 v[88:89], v[90:91], v[88:89]
	v_pk_add_f32 v[84:85], v[86:87], v[84:85]
	v_pk_add_f32 v[82:83], v[82:83], v[92:93]
	v_pk_add_f32 v[84:85], v[84:85], v[88:89]
	v_add_f32_e32 v82, v82, v83
	v_add_f32_e32 v83, v84, v85
	v_add_f32_e32 v82, v82, v83
	v_mov_b32_e32 v235, v82
	v_mov_b32_e32 v234, v82
	ds_read_b64_tr_b16 v[82:83], v225 offset:24576
	ds_read_b64_tr_b16 v[84:85], v225 offset:26112
	ds_read_b64_tr_b16 v[86:87], v225 offset:24640
	ds_read_b64_tr_b16 v[88:89], v225 offset:26176
	ds_read_b64_tr_b16 v[90:91], v225 offset:27648
	ds_read_b64_tr_b16 v[92:93], v225 offset:29184
	ds_read_b64_tr_b16 v[94:95], v225 offset:27712
	ds_read_b64_tr_b16 v[96:97], v225 offset:29248
	v_permlane32_swap_b32_e32 v235, v234
	v_add_f32_e32 v234, v234, v235
	v_fmac_f32_e32 v234, v190, v160
	v_mov_b32_e32 v190, v234
	v_cvt_pk_bf16_f32 v34, v34, v35
	v_cvt_pk_bf16_f32 v35, v36, v37
	v_cvt_pk_bf16_f32 v36, v38, v39
	v_cvt_pk_bf16_f32 v37, v40, v41
	v_cvt_pk_bf16_f32 v38, v42, v43
	v_cvt_pk_bf16_f32 v39, v44, v45
	v_cvt_pk_bf16_f32 v40, v46, v47
	v_cvt_pk_bf16_f32 v41, v48, v49
	v_cvt_pk_bf16_f32 v42, v50, v51
	v_cvt_pk_bf16_f32 v43, v52, v53
	v_cvt_pk_bf16_f32 v44, v54, v55
	v_cvt_pk_bf16_f32 v45, v56, v57
	v_cvt_pk_bf16_f32 v46, v58, v59
	v_cvt_pk_bf16_f32 v47, v60, v61
	v_cvt_pk_bf16_f32 v48, v62, v63
	v_cvt_pk_bf16_f32 v49, v64, v65
	s_waitcnt lgkmcnt(0)
	s_nop 0
	v_mfma_f32_32x32x16_bf16 v[18:33], v[66:69], v[34:37], v[18:33]
	v_mfma_f32_32x32x16_bf16 v[2:17], v[70:73], v[34:37], v[2:17]
	v_mfma_f32_32x32x16_bf16 v[18:33], v[74:77], v[38:41], v[18:33]
	v_mfma_f32_32x32x16_bf16 v[2:17], v[78:81], v[38:41], v[2:17]
	v_mfma_f32_32x32x16_bf16 v[18:33], v[82:85], v[42:45], v[18:33]
	v_mfma_f32_32x32x16_bf16 v[2:17], v[86:89], v[42:45], v[2:17]
	v_mfma_f32_32x32x16_bf16 v[18:33], v[90:93], v[46:49], v[18:33]
	v_mfma_f32_32x32x16_bf16 v[2:17], v[94:97], v[46:49], v[2:17]
	s_cmp_eq_u32 s18, 0
	s_cbranch_scc1 .Lp2_bot_11
	s_cmp_eq_u32 s19, 0
	s_cbranch_scc1 .Lp2_w0_12
	s_waitcnt vmcnt(1)
	s_branch .Lp2_w1_13

; #define LAS __attribute__((address_space(3)))
; template <int MODE  > ...
;     ...
;         const bool has_next = rem != 0ull; int jn = 0;
;         if (has_next) { jn = 63 - __builtin_clzll(rem); rem &= ~(1ull << jn);
;             kreg = *(const u32x4*)(Kg + (size_t)(64 * jn + skey) * 128 + schunk * 8);
;             if (NEEDV) vreg = *(const u32x4*)(Vg + (size_t)(64 * jn + skey) * 128 + schunk * 8); }
;         const bool selbit = (MODE == 1) ? (((selmask >> j) & 1ull) != 0ull) : true;
;         bool active = true;
;         if (MODE == 1) active = __builtin_amdgcn_ballot_w64(selbit) != 0ull;
;         if (active) {
;             const LAS bf16_t* kb = (const LAS bf16_t*)(lds + A_KBUF) + cur * 64 * KPITCH;
;             constexpr int STEP = CMPM ? 16 : 1;
;             const int Bint = CMPM ? (1024 * j + 31 - t + 64 * h) : (64 * j - t + 4 * h);
;             const float sl = slope2 * (float)STEP;
;             const float mref = st.m; const bool fresh = !(mref > -1e28f);
;             const float mest = fresh ? 0.f : mref;
;             const float basef = selbit ? (slope2 * (float)Bint - mest) : -1e30f;
;             int ptype;
;             if (MODE == 1) ptype = (j == cblk) ? 1 : 0;
;             else if (MODE == 2) ptype = (j == cblk) ? 1 : ((j == cblk - 8) ? 2 : 0);
;             else ptype = (64 * j + 63 <= 4 * cblk - 2) ? 0 : 1;
;             f32x16 s0, s1;
;             { const float sl2 = sl + sl, sl3 = sl2 + sl;
; #pragma unroll
;               for (int g8 = 0; g8 < 4; ++g8) {
;                   const float b0 = __builtin_fmaf(sl, (float)(8 * g8), basef), b1 = __builtin_fmaf(sl, (float)(8 * g8 + 32), basef);
;                   s0[4 * g8] = b0; s0[4 * g8 + 1] = b0 + sl; s0[4 * g8 + 2] = b0 + sl2; s0[4 * g8 + 3] = b0 + sl3;
;                   s1[4 * g8] = b1; s1[4 * g8 + 1] = b1 + sl; s1[4 * g8 + 2] = b1 + sl2; s1[4 * g8 + 3] = b1 + sl3;
;               } }
;             if (ptype == 1) {
;     ...
;         if (has_next) {
;             LAS bf16_t* kb = (LAS bf16_t*)(lds + A_KBUF) + (cur ^ 1) * 64 * KPITCH;
;             *(LAS u32x4*)(kb + skey * KPITCH + schunk * 8) = kreg;
;             if (NEEDV) { LAS bf16_t* vb = (LAS bf16_t*)(lds + A_VBUF) + (cur ^ 1) * 64 * VPITCH;
;                 *(LAS u32x4*)(vb + skey * VPITCH + schunk * 8) = vreg; }
;         }
;         __syncthreads();
;         if (!has_next) break;
;         j = jn; cur ^= 1;
;     }
.Lp2_w1_13:
	s_xor_b32 s14, s22, 1
	s_mul_i32 s14, s14, 0x3000
	v_add_u32_e32 v235, s14, v166
	ds_write_b128 v235, v[230:233] offset:18432
	s_cmp_eq_u32 s19, 0
	s_cbranch_scc1 .Lp2_bot_11
	s_mul_i32 s14, s22, 0x2400
	v_add_u32_e32 v234, s14, v165
	ds_write_b128 v234, v[130:133]
.Lp2_bot_11:
	s_xor_b32 s22, s22, 1
	s_waitcnt lgkmcnt(0)
	s_barrier
	s_cmp_eq_u32 s18, 0
	s_cbranch_scc1 .Lm2_exit
	s_mov_b32 s62, s4
	s_mov_b32 s18, s19
	s_branch .Lp2_int1
.Lp2_int1:
	s_mov_b32 s19, 0
	s_cmp_eq_u64 s[16:17], 0
	s_cbranch_scc1 .Lp2_noload_15
	s_flbit_i32_b64 s4, s[16:17]
	s_xor_b32 s4, s4, 63
	s_lshl_b64 vcc, 1, s4
	s_andn2_b64 s[16:17], s[16:17], vcc
	s_mov_b32 s19, 1
	v_lshl_add_u32 v50, s4, 6, v161
	v_ashrrev_i32_e32 v51, 31, v50
	v_lshlrev_b64 v[50:51], 8, v[50:51]
	v_lshl_add_u64 v[52:53], v[142:143], 0, v[50:51]
	v_lshl_add_u64 v[50:51], v[140:141], 0, v[50:51]
	global_load_dwordx4 v[226:229], v[52:53], off
	global_load_dwordx4 v[230:233], v[50:51], off
.Lp2_noload_15:
	s_xor_b32 vcc_lo, s22, 1
	s_mul_i32 vcc_lo, vcc_lo, 0x2400
	v_add_u32_e32 v254, vcc_lo, v188
	ds_read_b128 v[66:69], v254
	ds_read_b128 v[70:73], v254 offset:4608
	ds_read_b128 v[74:77], v254 offset:32
	ds_read_b128 v[78:81], v254 offset:4640
	ds_read_b128 v[82:85], v254 offset:64
	ds_read_b128 v[86:89], v254 offset:4672
	ds_read_b128 v[90:93], v254 offset:96
	ds_read_b128 v[94:97], v254 offset:4704
	v_lshl_add_u32 v1, s62, 6, v167
	v_cvt_f32_i32_e32 v50, v1
	v_cmp_nlt_f32_e64 s[14:15], s71, v192
	s_cmp_eq_u32 s62, s23
	s_cselect_b32 s21, 2, 0
	s_cmp_lg_u32 s62, s83
	s_cselect_b32 s68, s21, 1
	s_cmp_eq_u32 s68, 0
	v_cndmask_b32_e64 v224, v192, 0, s[14:15]
	v_fma_f32 v62, v186, v50, -v224
	v_fma_f32 v34, 0, v186, v62
	v_fmamk_f32 v38, v186, 0x41000000, v62
	v_fmamk_f32 v42, v186, 0x41800000, v62
	v_fmamk_f32 v46, v186, 0x41c00000, v62
	v_fmamk_f32 v50, v186, 0x42000000, v62
	v_fmamk_f32 v54, v186, 0x42200000, v62
	v_fmamk_f32 v58, v186, 0x42400000, v62
	v_fmac_f32_e32 v62, 0x42600000, v186
	v_add_f32_e32 v35, v186, v34
	v_add_f32_e32 v36, v187, v34
	v_add_f32_e32 v37, v163, v34
	v_add_f32_e32 v39, v186, v38
	v_add_f32_e32 v40, v187, v38
	v_add_f32_e32 v41, v163, v38
	v_add_f32_e32 v43, v186, v42
	v_add_f32_e32 v44, v187, v42
	v_add_f32_e32 v45, v163, v42
	v_add_f32_e32 v47, v186, v46
	v_add_f32_e32 v48, v187, v46
	v_add_f32_e32 v49, v163, v46
	v_add_f32_e32 v51, v186, v50
	v_add_f32_e32 v52, v187, v50
	v_add_f32_e32 v53, v163, v50
	v_add_f32_e32 v55, v186, v54
	v_add_f32_e32 v56, v187, v54
	v_add_f32_e32 v57, v163, v54
	v_add_f32_e32 v59, v186, v58
	v_add_f32_e32 v60, v187, v58
	v_add_f32_e32 v61, v163, v58
	v_add_f32_e32 v63, v186, v62
	v_add_f32_e32 v64, v187, v62
	v_add_f32_e32 v65, v163, v62
	s_cbranch_scc1 .Lp2_initdone_16
	s_cmp_eq_u32 s68, 1
	s_cbranch_scc1 .Lp2_edge1_17
	v_sub_f32_e32 v253, v162, v224
	v_cmp_gt_f32_e32 vcc, v34, v253
	s_nop 1
	v_cndmask_b32_e32 v34, v241, v34, vcc
	v_cmp_gt_f32_e32 vcc, v35, v253
	s_nop 1
	v_cndmask_b32_e32 v35, v241, v35, vcc
	v_cmp_gt_f32_e32 vcc, v36, v253
	s_nop 1
	v_cndmask_b32_e32 v36, v241, v36, vcc
	v_cmp_gt_f32_e32 vcc, v37, v253
	s_nop 1
	v_cndmask_b32_e32 v37, v241, v37, vcc
	v_cmp_gt_f32_e32 vcc, v38, v253
	s_nop 1
	v_cndmask_b32_e32 v38, v241, v38, vcc
	v_cmp_gt_f32_e32 vcc, v39, v253
	s_nop 1
	v_cndmask_b32_e32 v39, v241, v39, vcc
	v_cmp_gt_f32_e32 vcc, v40, v253
	s_nop 1
	v_cndmask_b32_e32 v40, v241, v40, vcc
	v_cmp_gt_f32_e32 vcc, v41, v253
	s_nop 1
	v_cndmask_b32_e32 v41, v241, v41, vcc
	v_cmp_gt_f32_e32 vcc, v42, v253
	s_nop 1
	v_cndmask_b32_e32 v42, v241, v42, vcc
	v_cmp_gt_f32_e32 vcc, v43, v253
	s_nop 1
	v_cndmask_b32_e32 v43, v241, v43, vcc
	v_cmp_gt_f32_e32 vcc, v44, v253
	s_nop 1
	v_cndmask_b32_e32 v44, v241, v44, vcc
	v_cmp_gt_f32_e32 vcc, v45, v253
	s_nop 1
	v_cndmask_b32_e32 v45, v241, v45, vcc
	v_cmp_gt_f32_e32 vcc, v46, v253
	s_nop 1
	v_cndmask_b32_e32 v46, v241, v46, vcc
	v_cmp_gt_f32_e32 vcc, v47, v253
	s_nop 1
	v_cndmask_b32_e32 v47, v241, v47, vcc
	v_cmp_gt_f32_e32 vcc, v48, v253
	s_nop 1
	v_cndmask_b32_e32 v48, v241, v48, vcc
	v_cmp_gt_f32_e32 vcc, v49, v253
	s_nop 1
	v_cndmask_b32_e32 v49, v241, v49, vcc
	v_cmp_gt_f32_e32 vcc, v50, v253
	s_nop 1
	v_cndmask_b32_e32 v50, v241, v50, vcc
	v_cmp_gt_f32_e32 vcc, v51, v253
	s_nop 1
	v_cndmask_b32_e32 v51, v241, v51, vcc
	v_cmp_gt_f32_e32 vcc, v52, v253
	s_nop 1
	v_cndmask_b32_e32 v52, v241, v52, vcc
	v_cmp_gt_f32_e32 vcc, v53, v253
	s_nop 1
	v_cndmask_b32_e32 v53, v241, v53, vcc
	v_cmp_gt_f32_e32 vcc, v54, v253
	s_nop 1
	v_cndmask_b32_e32 v54, v241, v54, vcc
	v_cmp_gt_f32_e32 vcc, v55, v253
	s_nop 1
	v_cndmask_b32_e32 v55, v241, v55, vcc
	v_cmp_gt_f32_e32 vcc, v56, v253
	s_nop 1
	v_cndmask_b32_e32 v56, v241, v56, vcc
	v_cmp_gt_f32_e32 vcc, v57, v253
	s_nop 1
	v_cndmask_b32_e32 v57, v241, v57, vcc
	v_cmp_gt_f32_e32 vcc, v58, v253
	s_nop 1
	v_cndmask_b32_e32 v58, v241, v58, vcc
	v_cmp_gt_f32_e32 vcc, v59, v253
	s_nop 1
	v_cndmask_b32_e32 v59, v241, v59, vcc
	v_cmp_gt_f32_e32 vcc, v60, v253
	s_nop 1
	v_cndmask_b32_e32 v60, v241, v60, vcc
	v_cmp_gt_f32_e32 vcc, v61, v253
	s_nop 1
	v_cndmask_b32_e32 v61, v241, v61, vcc
	v_cmp_gt_f32_e32 vcc, v62, v253
	s_nop 1
	v_cndmask_b32_e32 v62, v241, v62, vcc
	v_cmp_gt_f32_e32 vcc, v63, v253
	s_nop 1
	v_cndmask_b32_e32 v63, v241, v63, vcc
	v_cmp_gt_f32_e32 vcc, v64, v253
	s_nop 1
	v_cndmask_b32_e32 v64, v241, v64, vcc
	v_cmp_gt_f32_e32 vcc, v65, v253
	s_nop 1
	v_cndmask_b32_e32 v65, v241, v65, vcc
	s_branch .Lp2_initdone_16

; #define LAS __attribute__((address_space(3)))
; __device__ __forceinline__ float shflx(float v, int mask, int lane) { return __builtin_bit_cast(float, __builtin_amdgcn_ds_bpermute(((lane ^ mask) & 63) << 2, __builtin_bit_cast(int, v))); }
; template <int MODE  > ...
;     ...
;             for (int kk = 0; kk < 4; ++kk) {
;                 const bf16x8 k0 = *(const LAS bf16x8*)(kb + col * KPITCH + kk * 16 + h * 8);
;                 const bf16x8 k1 = *(const LAS bf16x8*)(kb + (32 + col) * KPITCH + kk * 16 + h * 8);
;                 s0 = __builtin_amdgcn_mfma_f32_32x32x16_bf16(k0, qf[kk], s0, 0, 0, 0);
;                 s1 = __builtin_amdgcn_mfma_f32_32x32x16_bf16(k1, qf[kk], s1, 0, 0, 0);
;             }
;             if (MODE != 3) {
;                 float mx = fmaxf(s0[0], s1[0]);
; #pragma unroll
;                 for (int i = 1; i < 16; ++i) mx = fmaxf(mx, fmaxf(s0[i], s1[i]));
;                 mx = fmaxf(mx, shflx(mx, 32, lane));
;                 float alpha = 1.f;
;                 if (__builtin_amdgcn_ballot_w64(fresh || mx > 0.f) != 0ull) {
;                     const float moldr = fresh ? -1e29f : 0.f, mnewr = fmaxf(moldr, mx);
;                     alpha = __builtin_amdgcn_exp2f(moldr - mnewr);
;                     st.m = mest + mnewr;
; #pragma unroll
;                     for (int i = 0; i < 16; ++i) { s0[i] = __builtin_amdgcn_exp2f(s0[i] - mnewr); s1[i] = __builtin_amdgcn_exp2f(s1[i] - mnewr); }
;                     st.o0 *= alpha; st.o1 *= alpha;
;                 } else {
; #pragma unroll
;                     for (int i = 0; i < 16; ++i) { s0[i] = __builtin_amdgcn_exp2f(s0[i]); s1[i] = __builtin_amdgcn_exp2f(s1[i]); }
;                 }
.Lp2_initdone_16:
	v_max3_f32 v234, v114, v115, v116
	v_max3_f32 v234, v234, v117, v118
	v_max3_f32 v234, v234, v119, v120
	v_max3_f32 v234, v234, v121, v122
	v_max3_f32 v234, v234, v123, v124
	v_max3_f32 v234, v234, v125, v126
	v_max3_f32 v234, v234, v127, v128
	v_max3_f32 v235, v98, v99, v100
	v_max3_f32 v235, v235, v101, v102
	v_max3_f32 v235, v235, v103, v104
	v_max3_f32 v235, v235, v105, v106
	v_max3_f32 v235, v235, v107, v108
	v_max3_f32 v235, v235, v109, v110
	v_max3_f32 v235, v235, v111, v112
	v_max3_f32 v234, v234, v129, v113
	v_max_f32_e32 v234, v234, v235
	v_mov_b32_e32 v235, v234
	v_sub_f32_e32 v253, v192, v252
	s_nop 0
	v_permlane32_swap_b32_e32 v235, v234
	v_max_f32_e32 v234, v234, v235
	v_cmp_lt_f32_e32 vcc, 0, v234
	v_cmp_lg_f32_e64 s[14:15], 0, v253
	s_nop 1
	s_or_b64 vcc, s[14:15], vcc
	s_cbranch_vccz .Lp2_fast_18
	v_max_f32_e32 v234, v253, v234
	v_sub_f32_e32 v235, v253, v234
	v_exp_f32_e32 v160, v235
	v_add_f32_e32 v192, v252, v234
	s_waitcnt lgkmcnt(7)
	v_mfma_f32_32x32x16_bf16 v[34:49], v[66:69], v[144:147], v[34:49]
	v_sub_f32_e32 v114, v114, v234
	v_exp_f32_e32 v114, v114
	v_sub_f32_e32 v115, v115, v234
	v_exp_f32_e32 v115, v115
	v_sub_f32_e32 v116, v116, v234
	v_exp_f32_e32 v116, v116
	v_sub_f32_e32 v117, v117, v234
	v_exp_f32_e32 v117, v117
	s_waitcnt lgkmcnt(6)
	v_mfma_f32_32x32x16_bf16 v[50:65], v[70:73], v[144:147], v[50:65]
	v_sub_f32_e32 v118, v118, v234
	v_exp_f32_e32 v118, v118
	v_sub_f32_e32 v119, v119, v234
	v_exp_f32_e32 v119, v119
	v_sub_f32_e32 v120, v120, v234
	v_exp_f32_e32 v120, v120
	v_sub_f32_e32 v121, v121, v234
	v_exp_f32_e32 v121, v121
	s_waitcnt lgkmcnt(5)
	v_mfma_f32_32x32x16_bf16 v[34:49], v[74:77], v[148:151], v[34:49]
	v_sub_f32_e32 v122, v122, v234
	v_exp_f32_e32 v122, v122
	v_sub_f32_e32 v123, v123, v234
	v_exp_f32_e32 v123, v123
	v_sub_f32_e32 v124, v124, v234
	v_exp_f32_e32 v124, v124
	v_sub_f32_e32 v125, v125, v234
	v_exp_f32_e32 v125, v125
	s_waitcnt lgkmcnt(4)
	v_mfma_f32_32x32x16_bf16 v[50:65], v[78:81], v[148:151], v[50:65]
	v_sub_f32_e32 v126, v126, v234
	v_exp_f32_e32 v126, v126
	v_sub_f32_e32 v127, v127, v234
	v_exp_f32_e32 v127, v127
	v_sub_f32_e32 v128, v128, v234
	v_exp_f32_e32 v128, v128
	v_sub_f32_e32 v129, v129, v234
	v_exp_f32_e32 v129, v129
	s_waitcnt lgkmcnt(3)
	v_mfma_f32_32x32x16_bf16 v[34:49], v[82:85], v[152:155], v[34:49]
	v_sub_f32_e32 v98, v98, v234
	v_exp_f32_e32 v98, v98
	v_sub_f32_e32 v99, v99, v234
	v_exp_f32_e32 v99, v99
	v_sub_f32_e32 v100, v100, v234
	v_exp_f32_e32 v100, v100
	v_sub_f32_e32 v101, v101, v234
	v_exp_f32_e32 v101, v101
	s_waitcnt lgkmcnt(2)
	v_mfma_f32_32x32x16_bf16 v[50:65], v[86:89], v[152:155], v[50:65]
	v_sub_f32_e32 v102, v102, v234
	v_exp_f32_e32 v102, v102
	v_sub_f32_e32 v103, v103, v234
	v_exp_f32_e32 v103, v103
	v_sub_f32_e32 v104, v104, v234
	v_exp_f32_e32 v104, v104
	v_sub_f32_e32 v105, v105, v234
	v_exp_f32_e32 v105, v105
	s_waitcnt lgkmcnt(1)
	v_mfma_f32_32x32x16_bf16 v[34:49], v[90:93], v[156:159], v[34:49]
	v_sub_f32_e32 v106, v106, v234
	v_exp_f32_e32 v106, v106
	v_sub_f32_e32 v107, v107, v234
	v_exp_f32_e32 v107, v107
	v_sub_f32_e32 v108, v108, v234
	v_exp_f32_e32 v108, v108
	v_sub_f32_e32 v109, v109, v234
	v_exp_f32_e32 v109, v109
	s_waitcnt lgkmcnt(0)
	v_mfma_f32_32x32x16_bf16 v[50:65], v[94:97], v[156:159], v[50:65]
	v_sub_f32_e32 v110, v110, v234
	v_exp_f32_e32 v110, v110
	v_sub_f32_e32 v111, v111, v234
	v_exp_f32_e32 v111, v111
	v_sub_f32_e32 v112, v112, v234
	v_exp_f32_e32 v112, v112
	v_sub_f32_e32 v113, v113, v234
	v_exp_f32_e32 v113, v113
	v_pk_mul_f32 v[18:19], v[18:19], v[160:161] op_sel_hi:[1,0]
	v_pk_mul_f32 v[20:21], v[20:21], v[160:161] op_sel_hi:[1,0]
	v_pk_mul_f32 v[22:23], v[22:23], v[160:161] op_sel_hi:[1,0]
	v_pk_mul_f32 v[24:25], v[24:25], v[160:161] op_sel_hi:[1,0]
	v_pk_mul_f32 v[26:27], v[26:27], v[160:161] op_sel_hi:[1,0]
	v_pk_mul_f32 v[28:29], v[28:29], v[160:161] op_sel_hi:[1,0]
	v_pk_mul_f32 v[30:31], v[30:31], v[160:161] op_sel_hi:[1,0]
	v_pk_mul_f32 v[32:33], v[32:33], v[160:161] op_sel_hi:[1,0]
	v_pk_mul_f32 v[2:3], v[2:3], v[160:161] op_sel_hi:[1,0]
	v_pk_mul_f32 v[4:5], v[4:5], v[160:161] op_sel_hi:[1,0]
	v_pk_mul_f32 v[6:7], v[6:7], v[160:161] op_sel_hi:[1,0]
	v_pk_mul_f32 v[8:9], v[8:9], v[160:161] op_sel_hi:[1,0]
	v_pk_mul_f32 v[10:11], v[10:11], v[160:161] op_sel_hi:[1,0]
	v_pk_mul_f32 v[12:13], v[12:13], v[160:161] op_sel_hi:[1,0]
	v_pk_mul_f32 v[14:15], v[14:15], v[160:161] op_sel_hi:[1,0]
	v_pk_mul_f32 v[16:17], v[16:17], v[160:161] op_sel_hi:[1,0]
	s_branch .Lp2_pv_19
; #define LAS __attribute__((address_space(3)))
; template <int MODE  > ...
;     ...
; #pragma unroll
;                     for (int i = 0; i < 16; ++i) { s0[i] = __builtin_amdgcn_exp2f(s0[i]); s1[i] = __builtin_amdgcn_exp2f(s1[i]); }
;                 }
;                 { typedef float f32x8 __attribute__((ext_vector_type(8)));
;                   const f32x16 t16 = s0 + s1;
;                   const f32x8 t8 = __builtin_shufflevector(t16, t16, 0, 1, 2, 3, 4, 5, 6, 7) + __builtin_shufflevector(t16, t16, 8, 9, 10, 11, 12, 13, 14, 15);
;                   const f32x4 t4 = __builtin_shufflevector(t8, t8, 0, 1, 2, 3) + __builtin_shufflevector(t8, t8, 4, 5, 6, 7);
;                   float ps = (t4[0] + t4[1]) + (t4[2] + t4[3]);
;                   ps += shflx(ps, 32, lane);
;                   st.l = st.l * alpha + ps; }
;                 bf16x8 pf[4];
; #pragma unroll
;                 for (int kk = 0; kk < 4; ++kk) {
;                     u32x4 pw;
;                     if (kk < 2) { pw.x = pk2(s0[8 * kk], s0[8 * kk + 1]); pw.y = pk2(s0[8 * kk + 2], s0[8 * kk + 3]); pw.z = pk2(s0[8 * kk + 4], s0[8 * kk + 5]); pw.w = pk2(s0[8 * kk + 6], s0[8 * kk + 7]); }
;                     else { const int k2 = kk - 2; pw.x = pk2(s1[8 * k2], s1[8 * k2 + 1]); pw.y = pk2(s1[8 * k2 + 2], s1[8 * k2 + 3]); pw.z = pk2(s1[8 * k2 + 4], s1[8 * k2 + 5]); pw.w = pk2(s1[8 * k2 + 6], s1[8 * k2 + 7]); }
;                     pf[kk] = __builtin_bit_cast(bf16x8, pw);
;                 }
;                 const LAS bf16_t* vb = (const LAS bf16_t*)(lds + A_VBUF) + cur * 64 * VPITCH + (4 * h + ((lane & 15) >> 2)) * VPITCH + ((lane >> 4) & 1) * 16 + 4 * (lane & 3);
; #pragma unroll
;                 for (int kk = 0; kk < 4; ++kk) {
;                     typedef short v4i16_t __attribute__((ext_vector_type(4)));
;                     const v4i16_t a0 = __builtin_amdgcn_ds_read_tr16_b64_v4i16((LAS v4i16_t*)(vb + (16 * kk) * VPITCH));
;                     const v4i16_t a1 = __builtin_amdgcn_ds_read_tr16_b64_v4i16((LAS v4i16_t*)(vb + (16 * kk + 8) * VPITCH));
;                     const v4i16_t b0 = __builtin_amdgcn_ds_read_tr16_b64_v4i16((LAS v4i16_t*)(vb + (16 * kk) * VPITCH + 32));
;                     const v4i16_t b1 = __builtin_amdgcn_ds_read_tr16_b64_v4i16((LAS v4i16_t*)(vb + (16 * kk + 8) * VPITCH + 32));
.Lp2_fast_18:
	s_waitcnt lgkmcnt(7)
	v_mfma_f32_32x32x16_bf16 v[34:49], v[66:69], v[144:147], v[34:49]
	v_exp_f32_e32 v114, v114
	v_exp_f32_e32 v115, v115
	v_exp_f32_e32 v116, v116
	v_exp_f32_e32 v117, v117
	s_waitcnt lgkmcnt(6)
	v_mfma_f32_32x32x16_bf16 v[50:65], v[70:73], v[144:147], v[50:65]
	v_exp_f32_e32 v118, v118
	v_exp_f32_e32 v119, v119
	v_exp_f32_e32 v120, v120
	v_exp_f32_e32 v121, v121
	s_waitcnt lgkmcnt(5)
	v_mfma_f32_32x32x16_bf16 v[34:49], v[74:77], v[148:151], v[34:49]
	v_exp_f32_e32 v122, v122
	v_exp_f32_e32 v123, v123
	v_exp_f32_e32 v124, v124
	v_exp_f32_e32 v125, v125
	s_waitcnt lgkmcnt(4)
	v_mfma_f32_32x32x16_bf16 v[50:65], v[78:81], v[148:151], v[50:65]
	v_exp_f32_e32 v126, v126
	v_exp_f32_e32 v127, v127
	v_exp_f32_e32 v128, v128
	v_exp_f32_e32 v129, v129
	s_waitcnt lgkmcnt(3)
	v_mfma_f32_32x32x16_bf16 v[34:49], v[82:85], v[152:155], v[34:49]
	v_exp_f32_e32 v98, v98
	v_exp_f32_e32 v99, v99
	v_exp_f32_e32 v100, v100
	v_exp_f32_e32 v101, v101
	s_waitcnt lgkmcnt(2)
	v_mfma_f32_32x32x16_bf16 v[50:65], v[86:89], v[152:155], v[50:65]
	v_exp_f32_e32 v102, v102
	v_exp_f32_e32 v103, v103
	v_exp_f32_e32 v104, v104
	v_exp_f32_e32 v105, v105
	s_waitcnt lgkmcnt(1)
	v_mfma_f32_32x32x16_bf16 v[34:49], v[90:93], v[156:159], v[34:49]
	v_exp_f32_e32 v106, v106
	v_exp_f32_e32 v107, v107
	v_exp_f32_e32 v108, v108
	v_exp_f32_e32 v109, v109
	s_waitcnt lgkmcnt(0)
	v_mfma_f32_32x32x16_bf16 v[50:65], v[94:97], v[156:159], v[50:65]
	v_exp_f32_e32 v110, v110
	v_exp_f32_e32 v111, v111
	v_exp_f32_e32 v112, v112
	v_exp_f32_e32 v113, v113
	v_mov_b32_e32 v160, 1.0
.Lp2_pv_19:
	s_mul_i32 vcc_hi, s22, 0x3000
	v_add_u32_e32 v225, vcc_hi, v191
	ds_read_b64_tr_b16 v[66:67], v225 offset:18432
	ds_read_b64_tr_b16 v[68:69], v225 offset:19968
	ds_read_b64_tr_b16 v[70:71], v225 offset:18496
	ds_read_b64_tr_b16 v[72:73], v225 offset:20032
	ds_read_b64_tr_b16 v[74:75], v225 offset:21504
	ds_read_b64_tr_b16 v[76:77], v225 offset:23040
	ds_read_b64_tr_b16 v[78:79], v225 offset:21568
	ds_read_b64_tr_b16 v[80:81], v225 offset:23104
	v_pk_add_f32 v[96:97], v[98:99], v[114:115]
	v_pk_add_f32 v[94:95], v[102:103], v[118:119]
	v_pk_add_f32 v[82:83], v[106:107], v[122:123]
	v_pk_add_f32 v[92:93], v[110:111], v[126:127]
	v_pk_add_f32 v[90:91], v[104:105], v[120:121]
	v_pk_add_f32 v[88:89], v[112:113], v[128:129]
	v_pk_add_f32 v[84:85], v[108:109], v[124:125]
	v_pk_add_f32 v[86:87], v[100:101], v[116:117]
	v_pk_add_f32 v[92:93], v[94:95], v[92:93]
	v_pk_add_f32 v[82:83], v[96:97], v[82:83]
	v_pk_add_f32 v[88:89], v[90:91], v[88:89]
	v_pk_add_f32 v[84:85], v[86:87], v[84:85]
	v_pk_add_f32 v[82:83], v[82:83], v[92:93]
	v_pk_add_f32 v[84:85], v[84:85], v[88:89]
	v_add_f32_e32 v82, v82, v83
	v_add_f32_e32 v83, v84, v85
	v_add_f32_e32 v82, v82, v83
	v_mov_b32_e32 v235, v82
	v_mov_b32_e32 v234, v82
	ds_read_b64_tr_b16 v[82:83], v225 offset:24576
	ds_read_b64_tr_b16 v[84:85], v225 offset:26112
	ds_read_b64_tr_b16 v[86:87], v225 offset:24640
	ds_read_b64_tr_b16 v[88:89], v225 offset:26176
	ds_read_b64_tr_b16 v[90:91], v225 offset:27648
	ds_read_b64_tr_b16 v[92:93], v225 offset:29184
	ds_read_b64_tr_b16 v[94:95], v225 offset:27712
	ds_read_b64_tr_b16 v[96:97], v225 offset:29248
	v_permlane32_swap_b32_e32 v235, v234
	v_add_f32_e32 v234, v234, v235
	v_fmac_f32_e32 v234, v190, v160
	v_mov_b32_e32 v190, v234
	v_cvt_pk_bf16_f32 v114, v114, v115
	v_cvt_pk_bf16_f32 v115, v116, v117
	v_cvt_pk_bf16_f32 v116, v118, v119
	v_cvt_pk_bf16_f32 v117, v120, v121
	v_cvt_pk_bf16_f32 v118, v122, v123
	v_cvt_pk_bf16_f32 v119, v124, v125
	v_cvt_pk_bf16_f32 v120, v126, v127
	v_cvt_pk_bf16_f32 v121, v128, v129
	v_cvt_pk_bf16_f32 v122, v98, v99
	v_cvt_pk_bf16_f32 v123, v100, v101
	v_cvt_pk_bf16_f32 v124, v102, v103
	v_cvt_pk_bf16_f32 v125, v104, v105
	v_cvt_pk_bf16_f32 v126, v106, v107
	v_cvt_pk_bf16_f32 v127, v108, v109
	v_cvt_pk_bf16_f32 v128, v110, v111
	v_cvt_pk_bf16_f32 v129, v112, v113
	s_waitcnt lgkmcnt(0)
	s_nop 0
	v_mfma_f32_32x32x16_bf16 v[18:33], v[66:69], v[114:117], v[18:33]
	v_mfma_f32_32x32x16_bf16 v[2:17], v[70:73], v[114:117], v[2:17]
	v_mfma_f32_32x32x16_bf16 v[18:33], v[74:77], v[118:121], v[18:33]
	v_mfma_f32_32x32x16_bf16 v[2:17], v[78:81], v[118:121], v[2:17]
	v_mfma_f32_32x32x16_bf16 v[18:33], v[82:85], v[122:125], v[18:33]
	v_mfma_f32_32x32x16_bf16 v[2:17], v[86:89], v[122:125], v[2:17]
	v_mfma_f32_32x32x16_bf16 v[18:33], v[90:93], v[126:129], v[18:33]
	v_mfma_f32_32x32x16_bf16 v[2:17], v[94:97], v[126:129], v[2:17]
	s_cmp_eq_u32 s18, 0
	s_cbranch_scc1 .Lp2_bot_20
	s_cmp_eq_u32 s19, 0
	s_cbranch_scc1 .Lp2_w0_21
	s_waitcnt vmcnt(1)
	s_branch .Lp2_w1_22

; #define LAS __attribute__((address_space(3)))
; template <int MODE  > ...
;     ...
;         if (has_next) {
;             LAS bf16_t* kb = (LAS bf16_t*)(lds + A_KBUF) + (cur ^ 1) * 64 * KPITCH;
;             *(LAS u32x4*)(kb + skey * KPITCH + schunk * 8) = kreg;
;             if (NEEDV) { LAS bf16_t* vb = (LAS bf16_t*)(lds + A_VBUF) + (cur ^ 1) * 64 * VPITCH;
;                 *(LAS u32x4*)(vb + skey * VPITCH + schunk * 8) = vreg; }
;         }
.Lp2_w1_22:
	s_xor_b32 s14, s22, 1
	s_mul_i32 s14, s14, 0x3000
	v_add_u32_e32 v235, s14, v166
	ds_write_b128 v235, v[134:137] offset:18432
	s_cmp_eq_u32 s19, 0
	s_cbranch_scc1 .Lp2_bot_20
	s_mul_i32 s14, s22, 0x2400
	v_add_u32_e32 v234, s14, v165
	ds_write_b128 v234, v[226:229]
